# residual epilogues (ffn_out/mix_out): the xb tiles of both 128-row halves are loaded together at the start of the epilogue (one load-latency exposure instead of two)
# baseline (speedup 1.0000x reference)
.LBB0_162:
	s_lshl_b32 s17, s17, 8
	v_lshl_or_b32 v172, s16, 8, v187
	v_add_u32_e32 v176, s17, v185
	v_ashrrev_i32_e32 v173, 31, v172
	v_lshlrev_b64 v[202:203], 1, v[172:173]
	v_ashrrev_i32_e32 v177, 31, v176
	v_lshl_add_u64 v[174:175], s[22:23], 0, v[202:203]
	v_lshlrev_b64 v[204:205], 11, v[176:177]
	v_lshl_add_u64 v[128:129], v[174:175], 0, v[204:205]
	global_load_dwordx4 v[194:197], v[128:129], off
	global_load_dwordx4 v[198:201], v[128:129], off offset:256
	v_or_b32_e32 v128, 16, v176
	v_or_b32_e32 v130, 32, v176
	v_or_b32_e32 v132, 48, v176
	v_ashrrev_i32_e32 v129, 31, v128
	v_ashrrev_i32_e32 v131, 31, v130
	v_ashrrev_i32_e32 v133, 31, v132
	v_lshlrev_b64 v[182:183], 11, v[128:129]
	v_lshlrev_b64 v[180:181], 11, v[130:131]
	v_lshlrev_b64 v[178:179], 11, v[132:133]
	v_lshl_add_u64 v[128:129], v[174:175], 0, v[182:183]
	v_lshl_add_u64 v[130:131], v[174:175], 0, v[180:181]
	v_lshl_add_u64 v[206:207], v[174:175], 0, v[178:179]
	global_load_dwordx4 v[148:151], v[128:129], off
	global_load_dwordx4 v[144:147], v[128:129], off offset:256
	global_load_dwordx4 v[140:143], v[130:131], off
	global_load_dwordx4 v[136:139], v[130:131], off offset:256
	global_load_dwordx4 v[132:135], v[206:207], off
	s_nop 0
	global_load_dwordx4 v[128:131], v[206:207], off offset:256
	v_lshlrev_b64 v[222:223], 11, v[176:177]
	v_lshl_add_u64 v[224:225], v[222:223], 0, s[44:45]
	v_lshl_add_u64 v[224:225], v[174:175], 0, v[224:225]
	global_load_dwordx4 v[232:235], v[224:225], off
	global_load_dwordx4 v[236:239], v[224:225], off offset:256
	v_lshl_add_u64 v[226:227], v[222:223], 0, s[46:47]
	v_lshl_add_u64 v[226:227], v[174:175], 0, v[226:227]
	global_load_dwordx4 v[240:243], v[226:227], off
	global_load_dwordx4 v[244:247], v[226:227], off offset:256
	v_lshl_add_u64 v[224:225], v[222:223], 0, s[48:49]
	v_lshl_add_u64 v[224:225], v[174:175], 0, v[224:225]
	global_load_dwordx4 v[248:251], v[224:225], off
	global_load_dwordx4 v[252:255], v[224:225], off offset:256
	v_lshl_add_u64 v[226:227], v[222:223], 0, s[50:51]
	v_lshl_add_u64 v[226:227], v[174:175], 0, v[226:227]
	global_load_dwordx4 v[214:217], v[226:227], off
	global_load_dwordx4 v[218:221], v[226:227], off offset:256
	v_and_b32_e32 v206, 64, v159
	v_xor_b32_e32 v193, 16, v159
	v_add_u32_e32 v206, 64, v206
	v_xor_b32_e32 v207, 32, v159
	v_cmp_lt_i32_e32 vcc, v193, v206
	v_lshl_add_u64 v[204:205], s[22:23], 0, v[204:205]
	v_lshl_add_u64 v[202:203], v[204:205], 0, v[202:203]
	v_cndmask_b32_e32 v193, v159, v193, vcc
	v_cmp_lt_i32_e32 vcc, v207, v206
	v_lshlrev_b32_e32 v193, 2, v193
	s_waitcnt vmcnt(0)
	v_lshlrev_b32_e32 v204, 16, v194
	v_and_b32_e32 v205, 0xffff0000, v194
	v_lshlrev_b32_e32 v194, 16, v195
	v_and_b32_e32 v195, 0xffff0000, v195
	v_cndmask_b32_e32 v212, v159, v207, vcc
	v_lshlrev_b32_e32 v206, 16, v196
	v_and_b32_e32 v207, 0xffff0000, v196
	v_lshlrev_b32_e32 v196, 16, v197
	v_and_b32_e32 v197, 0xffff0000, v197
	v_lshlrev_b32_e32 v210, 16, v200
	v_and_b32_e32 v211, 0xffff0000, v200
	v_lshlrev_b32_e32 v200, 16, v201
	v_and_b32_e32 v201, 0xffff0000, v201
	v_pk_fma_f32 v[126:127], v[126:127], 0.5, v[194:195] op_sel_hi:[1,0,1]
	v_pk_fma_f32 v[124:125], v[124:125], 0.5, v[204:205] op_sel_hi:[1,0,1]
	v_pk_fma_f32 v[122:123], v[122:123], 0.5, v[196:197] op_sel_hi:[1,0,1]
	v_pk_fma_f32 v[196:197], v[114:115], 0.5, v[200:201] op_sel_hi:[1,0,1]
	v_pk_mul_f32 v[114:115], v[126:127], v[126:127]
	v_pk_fma_f32 v[120:121], v[120:121], 0.5, v[206:207] op_sel_hi:[1,0,1]
	v_pk_fma_f32 v[114:115], v[124:125], v[124:125], v[114:115]
	v_lshlrev_b32_e32 v208, 16, v198
	v_and_b32_e32 v209, 0xffff0000, v198
	v_pk_fma_f32 v[114:115], v[120:121], v[120:121], v[114:115]
	v_lshlrev_b32_e32 v198, 16, v199
	v_and_b32_e32 v199, 0xffff0000, v199
	v_pk_fma_f32 v[116:117], v[116:117], 0.5, v[208:209] op_sel_hi:[1,0,1]
	v_pk_fma_f32 v[114:115], v[122:123], v[122:123], v[114:115]
	v_pk_fma_f32 v[118:119], v[118:119], 0.5, v[198:199] op_sel_hi:[1,0,1]
	v_pk_fma_f32 v[114:115], v[116:117], v[116:117], v[114:115]
	v_pk_fma_f32 v[194:195], v[112:113], 0.5, v[210:211] op_sel_hi:[1,0,1]
	v_pk_fma_f32 v[114:115], v[118:119], v[118:119], v[114:115]
	v_cvt_pk_bf16_f32 v112, v124, v125
	v_cvt_pk_bf16_f32 v113, v126, v127
	s_nop 0
	v_pk_fma_f32 v[114:115], v[194:195], v[194:195], v[114:115]
	s_nop 0
	v_pk_fma_f32 v[114:115], v[196:197], v[196:197], v[114:115]
	s_nop 0
	v_add_f32_e32 v124, v114, v115
	ds_bpermute_b32 v125, v193, v124
	v_cvt_pk_bf16_f32 v114, v120, v121
	v_cvt_pk_bf16_f32 v115, v122, v123
	global_store_dwordx4 v[202:203], v[112:115], off
	v_cvt_pk_bf16_f32 v116, v116, v117
	v_cvt_pk_bf16_f32 v117, v118, v119
	v_cvt_pk_bf16_f32 v118, v194, v195
	v_cvt_pk_bf16_f32 v119, v196, v197
	global_store_dwordx4 v[202:203], v[116:119], off offset:256
	s_waitcnt lgkmcnt(0)
	v_add_f32_e32 v113, v124, v125
	v_lshlrev_b32_e32 v112, 2, v212
	ds_bpermute_b32 v114, v112, v113
	s_and_saveexec_b64 s[54:55], s[8:9]
	s_cbranch_execz .LBB0_164
	s_waitcnt lgkmcnt(0)
	v_add_f32_e32 v113, v113, v114
	ds_write_b32 v188, v113

.LBB0_170:
	s_or_b64 exec, exec, s[54:55]
	s_waitcnt lgkmcnt(0)
	v_lshlrev_b64 v[64:65], 11, v[176:177]
	v_lshl_add_u64 v[102:103], v[64:65], 0, s[44:45]
	v_lshl_add_u64 v[66:67], v[174:175], 0, v[102:103]
	v_mov_b32_e32 v94, v232
	v_mov_b32_e32 v95, v233
	v_mov_b32_e32 v96, v234
	v_mov_b32_e32 v97, v235
	v_mov_b32_e32 v98, v236
	v_mov_b32_e32 v99, v237
	v_mov_b32_e32 v100, v238
	v_mov_b32_e32 v101, v239
	v_lshl_add_u64 v[92:93], v[64:65], 0, s[46:47]
	v_lshl_add_u64 v[90:91], v[64:65], 0, s[48:49]
	v_lshl_add_u64 v[88:89], v[64:65], 0, s[50:51]
	v_lshl_add_u64 v[64:65], v[174:175], 0, v[92:93]
	v_lshl_add_u64 v[66:67], v[174:175], 0, v[90:91]
	v_lshl_add_u64 v[104:105], v[174:175], 0, v[88:89]
	v_mov_b32_e32 v84, v240
	v_mov_b32_e32 v85, v241
	v_mov_b32_e32 v86, v242
	v_mov_b32_e32 v87, v243
	v_mov_b32_e32 v80, v244
	v_mov_b32_e32 v81, v245
	v_mov_b32_e32 v82, v246
	v_mov_b32_e32 v83, v247
	v_mov_b32_e32 v76, v248
	v_mov_b32_e32 v77, v249
	v_mov_b32_e32 v78, v250
	v_mov_b32_e32 v79, v251
	v_mov_b32_e32 v72, v252
	v_mov_b32_e32 v73, v253
	v_mov_b32_e32 v74, v254
	v_mov_b32_e32 v75, v255
	v_mov_b32_e32 v68, v214
	v_mov_b32_e32 v69, v215
	v_mov_b32_e32 v70, v216
	v_mov_b32_e32 v71, v217
	s_nop 0
	v_mov_b32_e32 v64, v218
	v_mov_b32_e32 v65, v219
	v_mov_b32_e32 v66, v220
	v_mov_b32_e32 v67, v221
	v_lshlrev_b32_e32 v104, 16, v94
	v_and_b32_e32 v105, 0xffff0000, v94
	v_lshlrev_b32_e32 v94, 16, v95
	v_and_b32_e32 v95, 0xffff0000, v95
	v_lshlrev_b32_e32 v106, 16, v96
	v_and_b32_e32 v107, 0xffff0000, v96
	v_lshlrev_b32_e32 v96, 16, v97
	v_and_b32_e32 v97, 0xffff0000, v97
	v_lshlrev_b32_e32 v108, 16, v98
	v_and_b32_e32 v109, 0xffff0000, v98
	v_lshlrev_b32_e32 v98, 16, v99
	v_and_b32_e32 v99, 0xffff0000, v99
	v_lshlrev_b32_e32 v110, 16, v100
	v_and_b32_e32 v111, 0xffff0000, v100
	v_pk_fma_f32 v[62:63], v[62:63], 0.5, v[94:95] op_sel_hi:[1,0,1]
	v_pk_fma_f32 v[60:61], v[60:61], 0.5, v[104:105] op_sel_hi:[1,0,1]
	v_pk_fma_f32 v[58:59], v[58:59], 0.5, v[96:97] op_sel_hi:[1,0,1]
	v_pk_fma_f32 v[96:97], v[54:55], 0.5, v[98:99] op_sel_hi:[1,0,1]
	v_pk_fma_f32 v[98:99], v[48:49], 0.5, v[110:111] op_sel_hi:[1,0,1]
	v_pk_mul_f32 v[48:49], v[62:63], v[62:63]
	v_pk_fma_f32 v[56:57], v[56:57], 0.5, v[106:107] op_sel_hi:[1,0,1]
	v_pk_fma_f32 v[48:49], v[60:61], v[60:61], v[48:49]
	v_pk_fma_f32 v[94:95], v[52:53], 0.5, v[108:109] op_sel_hi:[1,0,1]
	v_pk_fma_f32 v[48:49], v[56:57], v[56:57], v[48:49]
	v_lshlrev_b32_e32 v100, 16, v101
	v_pk_fma_f32 v[48:49], v[58:59], v[58:59], v[48:49]
	v_and_b32_e32 v101, 0xffff0000, v101
	v_pk_fma_f32 v[48:49], v[94:95], v[94:95], v[48:49]
	v_cvt_pk_bf16_f32 v52, v60, v61
	v_cvt_pk_bf16_f32 v53, v62, v63
	v_cvt_pk_bf16_f32 v54, v56, v57
	v_pk_fma_f32 v[56:57], v[50:51], 0.5, v[100:101] op_sel_hi:[1,0,1]
	v_pk_fma_f32 v[48:49], v[96:97], v[96:97], v[48:49]
	v_cvt_pk_bf16_f32 v55, v58, v59
	s_nop 0
	v_pk_fma_f32 v[48:49], v[98:99], v[98:99], v[48:49]
	s_nop 0
	v_pk_fma_f32 v[48:49], v[56:57], v[56:57], v[48:49]
	s_nop 0
	v_add_f32_e32 v51, v48, v49
	ds_bpermute_b32 v60, v193, v51
	v_lshl_add_u64 v[48:49], s[22:23], 0, v[102:103]
	v_lshl_add_u64 v[58:59], v[172:173], 1, v[48:49]
	global_store_dwordx4 v[58:59], v[52:55], off
	v_cvt_pk_bf16_f32 v50, v94, v95
	s_waitcnt lgkmcnt(0)
	v_add_f32_e32 v48, v51, v60
	ds_bpermute_b32 v49, v112, v48
	v_cvt_pk_bf16_f32 v51, v96, v97
	v_cvt_pk_bf16_f32 v52, v98, v99
	v_cvt_pk_bf16_f32 v53, v56, v57
	global_store_dwordx4 v[58:59], v[50:53], off offset:256
	s_and_saveexec_b64 s[54:55], s[8:9]
	s_cbranch_execz .LBB0_172
	s_waitcnt lgkmcnt(0)
	v_add_f32_e32 v48, v48, v49
	ds_write_b32 v188, v48 offset:2048
.LBB0_172:
	s_or_b64 exec, exec, s[54:55]
	v_lshlrev_b32_e32 v50, 16, v85
	v_and_b32_e32 v51, 0xffff0000, v85
	v_lshlrev_b32_e32 v48, 16, v84
	s_waitcnt lgkmcnt(0)
	v_and_b32_e32 v49, 0xffff0000, v84
	v_pk_fma_f32 v[46:47], v[46:47], 0.5, v[50:51] op_sel_hi:[1,0,1]
	v_pk_fma_f32 v[48:49], v[44:45], 0.5, v[48:49] op_sel_hi:[1,0,1]
	v_pk_mul_f32 v[50:51], v[46:47], v[46:47]
	v_cvt_pk_bf16_f32 v44, v48, v49
	v_cvt_pk_bf16_f32 v45, v46, v47
	v_lshlrev_b32_e32 v46, 16, v86
	v_and_b32_e32 v47, 0xffff0000, v86
	v_pk_fma_f32 v[48:49], v[48:49], v[48:49], v[50:51]
	v_pk_fma_f32 v[40:41], v[40:41], 0.5, v[46:47] op_sel_hi:[1,0,1]
	s_nop 0
	v_pk_fma_f32 v[48:49], v[40:41], v[40:41], v[48:49]
	v_cvt_pk_bf16_f32 v46, v40, v41
	v_lshlrev_b32_e32 v40, 16, v87
	v_and_b32_e32 v41, 0xffff0000, v87
	v_pk_fma_f32 v[40:41], v[42:43], 0.5, v[40:41] op_sel_hi:[1,0,1]
	s_nop 0
	v_pk_fma_f32 v[42:43], v[40:41], v[40:41], v[48:49]
	v_cvt_pk_bf16_f32 v47, v40, v41
	v_lshlrev_b32_e32 v40, 16, v80
	v_and_b32_e32 v41, 0xffff0000, v80
	v_pk_fma_f32 v[36:37], v[36:37], 0.5, v[40:41] op_sel_hi:[1,0,1]
	s_nop 0
	v_pk_fma_f32 v[40:41], v[36:37], v[36:37], v[42:43]
	v_lshlrev_b32_e32 v42, 16, v81
	v_and_b32_e32 v43, 0xffff0000, v81
	v_pk_fma_f32 v[38:39], v[38:39], 0.5, v[42:43] op_sel_hi:[1,0,1]
	v_lshlrev_b32_e32 v42, 16, v82
	v_and_b32_e32 v43, 0xffff0000, v82
	v_pk_fma_f32 v[40:41], v[38:39], v[38:39], v[40:41]
	v_pk_fma_f32 v[42:43], v[32:33], 0.5, v[42:43] op_sel_hi:[1,0,1]
	s_nop 0
	v_pk_fma_f32 v[32:33], v[42:43], v[42:43], v[40:41]
	v_lshlrev_b32_e32 v40, 16, v83
	v_and_b32_e32 v41, 0xffff0000, v83
	v_pk_fma_f32 v[40:41], v[34:35], 0.5, v[40:41] op_sel_hi:[1,0,1]
	s_nop 0
	v_pk_fma_f32 v[32:33], v[40:41], v[40:41], v[32:33]
	s_nop 0
	v_add_f32_e32 v35, v32, v33
	ds_bpermute_b32 v50, v193, v35
	v_lshl_add_u64 v[32:33], s[22:23], 0, v[92:93]
	v_lshl_add_u64 v[48:49], v[172:173], 1, v[32:33]
	global_store_dwordx4 v[48:49], v[44:47], off
	v_cvt_pk_bf16_f32 v34, v36, v37
	s_waitcnt lgkmcnt(0)
	v_add_f32_e32 v32, v35, v50
	ds_bpermute_b32 v33, v112, v32
	v_cvt_pk_bf16_f32 v35, v38, v39
	v_cvt_pk_bf16_f32 v36, v42, v43
	v_cvt_pk_bf16_f32 v37, v40, v41
	global_store_dwordx4 v[48:49], v[34:37], off offset:256
	s_and_saveexec_b64 s[54:55], s[8:9]
	s_cbranch_execz .LBB0_174
	s_waitcnt lgkmcnt(0)
	v_add_f32_e32 v32, v32, v33
	ds_write_b32 v188, v32 offset:2304
.LBB0_174:
	s_or_b64 exec, exec, s[54:55]
	v_lshlrev_b32_e32 v34, 16, v77
	v_and_b32_e32 v35, 0xffff0000, v77
	v_lshlrev_b32_e32 v32, 16, v76
	s_waitcnt lgkmcnt(0)
	v_and_b32_e32 v33, 0xffff0000, v76
	v_pk_fma_f32 v[30:31], v[30:31], 0.5, v[34:35] op_sel_hi:[1,0,1]
	v_pk_fma_f32 v[32:33], v[28:29], 0.5, v[32:33] op_sel_hi:[1,0,1]
	v_pk_mul_f32 v[34:35], v[30:31], v[30:31]
	v_cvt_pk_bf16_f32 v28, v32, v33
	v_cvt_pk_bf16_f32 v29, v30, v31
	v_lshlrev_b32_e32 v30, 16, v78
	v_and_b32_e32 v31, 0xffff0000, v78
	v_pk_fma_f32 v[32:33], v[32:33], v[32:33], v[34:35]
	v_pk_fma_f32 v[24:25], v[24:25], 0.5, v[30:31] op_sel_hi:[1,0,1]
	s_nop 0
	v_pk_fma_f32 v[32:33], v[24:25], v[24:25], v[32:33]
	v_cvt_pk_bf16_f32 v30, v24, v25
	v_lshlrev_b32_e32 v24, 16, v79
	v_and_b32_e32 v25, 0xffff0000, v79
	v_pk_fma_f32 v[24:25], v[26:27], 0.5, v[24:25] op_sel_hi:[1,0,1]
	s_nop 0
	v_pk_fma_f32 v[26:27], v[24:25], v[24:25], v[32:33]
	v_cvt_pk_bf16_f32 v31, v24, v25
	v_lshlrev_b32_e32 v24, 16, v72
	v_and_b32_e32 v25, 0xffff0000, v72
	v_pk_fma_f32 v[20:21], v[20:21], 0.5, v[24:25] op_sel_hi:[1,0,1]
	s_nop 0
	v_pk_fma_f32 v[24:25], v[20:21], v[20:21], v[26:27]
	v_lshlrev_b32_e32 v26, 16, v73
	v_and_b32_e32 v27, 0xffff0000, v73
	v_pk_fma_f32 v[22:23], v[22:23], 0.5, v[26:27] op_sel_hi:[1,0,1]
	v_lshlrev_b32_e32 v26, 16, v74
	v_and_b32_e32 v27, 0xffff0000, v74
	v_pk_fma_f32 v[24:25], v[22:23], v[22:23], v[24:25]
	v_pk_fma_f32 v[26:27], v[16:17], 0.5, v[26:27] op_sel_hi:[1,0,1]
	s_nop 0
	v_pk_fma_f32 v[16:17], v[26:27], v[26:27], v[24:25]
	v_lshlrev_b32_e32 v24, 16, v75
	v_and_b32_e32 v25, 0xffff0000, v75
	v_pk_fma_f32 v[24:25], v[18:19], 0.5, v[24:25] op_sel_hi:[1,0,1]
	s_nop 0
	v_pk_fma_f32 v[16:17], v[24:25], v[24:25], v[16:17]
	s_nop 0
	v_add_f32_e32 v19, v16, v17
	ds_bpermute_b32 v34, v193, v19
	v_lshl_add_u64 v[16:17], s[22:23], 0, v[90:91]
	v_lshl_add_u64 v[32:33], v[172:173], 1, v[16:17]
	global_store_dwordx4 v[32:33], v[28:31], off
	v_cvt_pk_bf16_f32 v18, v20, v21
	s_waitcnt lgkmcnt(0)
	v_add_f32_e32 v16, v19, v34
	ds_bpermute_b32 v17, v112, v16
	v_cvt_pk_bf16_f32 v19, v22, v23
	v_cvt_pk_bf16_f32 v20, v26, v27
	v_cvt_pk_bf16_f32 v21, v24, v25
	global_store_dwordx4 v[32:33], v[18:21], off offset:256
	s_and_saveexec_b64 s[54:55], s[8:9]
	s_cbranch_execz .LBB0_176
	s_waitcnt lgkmcnt(0)
	v_add_f32_e32 v16, v16, v17
	ds_write_b32 v188, v16 offset:2560
.LBB0_176:
	s_or_b64 exec, exec, s[54:55]
	v_lshlrev_b32_e32 v18, 16, v69
	v_and_b32_e32 v19, 0xffff0000, v69
	v_lshlrev_b32_e32 v16, 16, v68
	s_waitcnt lgkmcnt(0)
	v_and_b32_e32 v17, 0xffff0000, v68
	v_pk_fma_f32 v[14:15], v[14:15], 0.5, v[18:19] op_sel_hi:[1,0,1]
	v_pk_fma_f32 v[16:17], v[12:13], 0.5, v[16:17] op_sel_hi:[1,0,1]
	v_pk_mul_f32 v[18:19], v[14:15], v[14:15]
	v_cvt_pk_bf16_f32 v12, v16, v17
	v_cvt_pk_bf16_f32 v13, v14, v15
	v_lshlrev_b32_e32 v14, 16, v70
	v_and_b32_e32 v15, 0xffff0000, v70
	v_pk_fma_f32 v[16:17], v[16:17], v[16:17], v[18:19]
	v_pk_fma_f32 v[8:9], v[8:9], 0.5, v[14:15] op_sel_hi:[1,0,1]
	s_nop 0
	v_pk_fma_f32 v[16:17], v[8:9], v[8:9], v[16:17]
	v_cvt_pk_bf16_f32 v14, v8, v9
	v_lshlrev_b32_e32 v8, 16, v71
	v_and_b32_e32 v9, 0xffff0000, v71
	v_pk_fma_f32 v[8:9], v[10:11], 0.5, v[8:9] op_sel_hi:[1,0,1]
	s_nop 0
	v_pk_fma_f32 v[10:11], v[8:9], v[8:9], v[16:17]
	v_cvt_pk_bf16_f32 v15, v8, v9
	v_lshlrev_b32_e32 v8, 16, v64
	v_and_b32_e32 v9, 0xffff0000, v64
	v_pk_fma_f32 v[4:5], v[4:5], 0.5, v[8:9] op_sel_hi:[1,0,1]
	s_nop 0
	v_pk_fma_f32 v[8:9], v[4:5], v[4:5], v[10:11]
	v_lshlrev_b32_e32 v10, 16, v65
	v_and_b32_e32 v11, 0xffff0000, v65
	v_pk_fma_f32 v[6:7], v[6:7], 0.5, v[10:11] op_sel_hi:[1,0,1]
	v_lshlrev_b32_e32 v10, 16, v66
	v_and_b32_e32 v11, 0xffff0000, v66
	v_pk_fma_f32 v[8:9], v[6:7], v[6:7], v[8:9]
	v_pk_fma_f32 v[10:11], v[0:1], 0.5, v[10:11] op_sel_hi:[1,0,1]
	s_nop 0
	v_pk_fma_f32 v[0:1], v[10:11], v[10:11], v[8:9]
	v_lshlrev_b32_e32 v8, 16, v67
	v_and_b32_e32 v9, 0xffff0000, v67
	v_pk_fma_f32 v[8:9], v[2:3], 0.5, v[8:9] op_sel_hi:[1,0,1]
	s_nop 0
	v_pk_fma_f32 v[0:1], v[8:9], v[8:9], v[0:1]
	s_nop 0
	v_add_f32_e32 v3, v0, v1
	ds_bpermute_b32 v18, v193, v3
	v_lshl_add_u64 v[0:1], s[22:23], 0, v[88:89]
	v_lshl_add_u64 v[16:17], v[172:173], 1, v[0:1]
	global_store_dwordx4 v[16:17], v[12:15], off
	v_cvt_pk_bf16_f32 v2, v4, v5
	s_waitcnt lgkmcnt(0)
	v_add_f32_e32 v0, v3, v18
	ds_bpermute_b32 v1, v112, v0
	v_cvt_pk_bf16_f32 v3, v6, v7
	v_cvt_pk_bf16_f32 v4, v10, v11
	v_cvt_pk_bf16_f32 v5, v8, v9
	global_store_dwordx4 v[16:17], v[2:5], off offset:256
	s_and_saveexec_b64 s[54:55], s[8:9]
	s_cbranch_execz .LBB0_178
	s_waitcnt lgkmcnt(0)
	v_add_f32_e32 v0, v0, v1
	ds_write_b32 v188, v0 offset:2816

.LBB0_443:
	s_lshl_b32 s15, s58, 8
	v_lshl_or_b32 v172, s14, 8, v187
	v_add_u32_e32 v176, s15, v185
	v_ashrrev_i32_e32 v173, 31, v172
	v_lshlrev_b64 v[202:203], 1, v[172:173]
	v_ashrrev_i32_e32 v177, 31, v176
	v_lshl_add_u64 v[174:175], s[20:21], 0, v[202:203]
	v_lshlrev_b64 v[204:205], 11, v[176:177]
	v_lshl_add_u64 v[128:129], v[174:175], 0, v[204:205]
	global_load_dwordx4 v[194:197], v[128:129], off
	global_load_dwordx4 v[198:201], v[128:129], off offset:256
	v_or_b32_e32 v128, 16, v176
	v_or_b32_e32 v130, 32, v176
	v_or_b32_e32 v132, 48, v176
	v_ashrrev_i32_e32 v129, 31, v128
	v_ashrrev_i32_e32 v131, 31, v130
	v_ashrrev_i32_e32 v133, 31, v132
	v_lshlrev_b64 v[182:183], 11, v[128:129]
	v_lshlrev_b64 v[180:181], 11, v[130:131]
	v_lshlrev_b64 v[178:179], 11, v[132:133]
	v_lshl_add_u64 v[128:129], v[174:175], 0, v[182:183]
	v_lshl_add_u64 v[130:131], v[174:175], 0, v[180:181]
	v_lshl_add_u64 v[206:207], v[174:175], 0, v[178:179]
	global_load_dwordx4 v[148:151], v[128:129], off
	global_load_dwordx4 v[144:147], v[128:129], off offset:256
	global_load_dwordx4 v[140:143], v[130:131], off
	global_load_dwordx4 v[136:139], v[130:131], off offset:256
	global_load_dwordx4 v[132:135], v[206:207], off
	s_nop 0
	global_load_dwordx4 v[128:131], v[206:207], off offset:256
	v_lshlrev_b64 v[222:223], 11, v[176:177]
	v_lshl_add_u64 v[224:225], v[222:223], 0, s[30:31]
	v_lshl_add_u64 v[224:225], v[174:175], 0, v[224:225]
	global_load_dwordx4 v[232:235], v[224:225], off
	global_load_dwordx4 v[236:239], v[224:225], off offset:256
	v_lshl_add_u64 v[226:227], v[222:223], 0, s[44:45]
	v_lshl_add_u64 v[226:227], v[174:175], 0, v[226:227]
	global_load_dwordx4 v[240:243], v[226:227], off
	global_load_dwordx4 v[244:247], v[226:227], off offset:256
	v_lshl_add_u64 v[224:225], v[222:223], 0, s[46:47]
	v_lshl_add_u64 v[224:225], v[174:175], 0, v[224:225]
	global_load_dwordx4 v[248:251], v[224:225], off
	global_load_dwordx4 v[252:255], v[224:225], off offset:256
	v_lshl_add_u64 v[226:227], v[222:223], 0, s[48:49]
	v_lshl_add_u64 v[226:227], v[174:175], 0, v[226:227]
	global_load_dwordx4 v[214:217], v[226:227], off
	global_load_dwordx4 v[218:221], v[226:227], off offset:256
	v_and_b32_e32 v206, 64, v159
	v_xor_b32_e32 v193, 16, v159
	v_add_u32_e32 v206, 64, v206
	v_xor_b32_e32 v207, 32, v159
	v_cmp_lt_i32_e32 vcc, v193, v206
	v_lshl_add_u64 v[204:205], s[20:21], 0, v[204:205]
	v_lshl_add_u64 v[202:203], v[204:205], 0, v[202:203]
	v_cndmask_b32_e32 v193, v159, v193, vcc
	v_cmp_lt_i32_e32 vcc, v207, v206
	v_lshlrev_b32_e32 v193, 2, v193
	s_waitcnt vmcnt(0)
	v_lshlrev_b32_e32 v204, 16, v194
	v_and_b32_e32 v205, 0xffff0000, v194
	v_lshlrev_b32_e32 v194, 16, v195
	v_and_b32_e32 v195, 0xffff0000, v195
	v_cndmask_b32_e32 v212, v159, v207, vcc
	v_lshlrev_b32_e32 v206, 16, v196
	v_and_b32_e32 v207, 0xffff0000, v196
	v_lshlrev_b32_e32 v196, 16, v197
	v_and_b32_e32 v197, 0xffff0000, v197
	v_lshlrev_b32_e32 v210, 16, v200
	v_and_b32_e32 v211, 0xffff0000, v200
	v_lshlrev_b32_e32 v200, 16, v201
	v_and_b32_e32 v201, 0xffff0000, v201
	v_pk_add_f32 v[126:127], v[126:127], v[194:195]
	v_pk_add_f32 v[124:125], v[124:125], v[204:205]
	v_pk_add_f32 v[122:123], v[122:123], v[196:197]
	v_pk_add_f32 v[196:197], v[114:115], v[200:201]
	v_pk_mul_f32 v[114:115], v[126:127], v[126:127]
	v_pk_add_f32 v[120:121], v[120:121], v[206:207]
	v_pk_fma_f32 v[114:115], v[124:125], v[124:125], v[114:115]
	v_lshlrev_b32_e32 v208, 16, v198
	v_and_b32_e32 v209, 0xffff0000, v198
	v_pk_fma_f32 v[114:115], v[120:121], v[120:121], v[114:115]
	v_lshlrev_b32_e32 v198, 16, v199
	v_and_b32_e32 v199, 0xffff0000, v199
	v_pk_add_f32 v[116:117], v[116:117], v[208:209]
	v_pk_fma_f32 v[114:115], v[122:123], v[122:123], v[114:115]
	v_pk_add_f32 v[118:119], v[118:119], v[198:199]
	v_pk_fma_f32 v[114:115], v[116:117], v[116:117], v[114:115]
	v_pk_add_f32 v[194:195], v[112:113], v[210:211]
	v_pk_fma_f32 v[114:115], v[118:119], v[118:119], v[114:115]
	v_cvt_pk_bf16_f32 v112, v124, v125
	v_cvt_pk_bf16_f32 v113, v126, v127
	s_nop 0
	v_pk_fma_f32 v[114:115], v[194:195], v[194:195], v[114:115]
	s_nop 0
	v_pk_fma_f32 v[114:115], v[196:197], v[196:197], v[114:115]
	s_nop 0
	v_add_f32_e32 v124, v114, v115
	ds_bpermute_b32 v125, v193, v124
	v_cvt_pk_bf16_f32 v114, v120, v121
	v_cvt_pk_bf16_f32 v115, v122, v123
	global_store_dwordx4 v[202:203], v[112:115], off
	v_cvt_pk_bf16_f32 v116, v116, v117
	v_cvt_pk_bf16_f32 v117, v118, v119
	v_cvt_pk_bf16_f32 v118, v194, v195
	v_cvt_pk_bf16_f32 v119, v196, v197
	global_store_dwordx4 v[202:203], v[116:119], off offset:256
	s_waitcnt lgkmcnt(0)
	v_add_f32_e32 v113, v124, v125
	v_lshlrev_b32_e32 v112, 2, v212
	ds_bpermute_b32 v114, v112, v113
	s_and_saveexec_b64 s[58:59], s[8:9]
	s_cbranch_execz .LBB0_445
	s_waitcnt lgkmcnt(0)
	v_add_f32_e32 v113, v113, v114
	ds_write_b32 v188, v113

.LBB0_451:
	s_or_b64 exec, exec, s[58:59]
	s_waitcnt lgkmcnt(0)
	v_lshlrev_b64 v[64:65], 11, v[176:177]
	v_lshl_add_u64 v[102:103], v[64:65], 0, s[30:31]
	v_lshl_add_u64 v[66:67], v[174:175], 0, v[102:103]
	v_mov_b32_e32 v94, v232
	v_mov_b32_e32 v95, v233
	v_mov_b32_e32 v96, v234
	v_mov_b32_e32 v97, v235
	v_mov_b32_e32 v98, v236
	v_mov_b32_e32 v99, v237
	v_mov_b32_e32 v100, v238
	v_mov_b32_e32 v101, v239
	v_lshl_add_u64 v[92:93], v[64:65], 0, s[44:45]
	v_lshl_add_u64 v[90:91], v[64:65], 0, s[46:47]
	v_lshl_add_u64 v[88:89], v[64:65], 0, s[48:49]
	v_lshl_add_u64 v[64:65], v[174:175], 0, v[92:93]
	v_lshl_add_u64 v[66:67], v[174:175], 0, v[90:91]
	v_lshl_add_u64 v[104:105], v[174:175], 0, v[88:89]
	v_mov_b32_e32 v84, v240
	v_mov_b32_e32 v85, v241
	v_mov_b32_e32 v86, v242
	v_mov_b32_e32 v87, v243
	v_mov_b32_e32 v80, v244
	v_mov_b32_e32 v81, v245
	v_mov_b32_e32 v82, v246
	v_mov_b32_e32 v83, v247
	v_mov_b32_e32 v76, v248
	v_mov_b32_e32 v77, v249
	v_mov_b32_e32 v78, v250
	v_mov_b32_e32 v79, v251
	v_mov_b32_e32 v72, v252
	v_mov_b32_e32 v73, v253
	v_mov_b32_e32 v74, v254
	v_mov_b32_e32 v75, v255
	v_mov_b32_e32 v68, v214
	v_mov_b32_e32 v69, v215
	v_mov_b32_e32 v70, v216
	v_mov_b32_e32 v71, v217
	s_nop 0
	v_mov_b32_e32 v64, v218
	v_mov_b32_e32 v65, v219
	v_mov_b32_e32 v66, v220
	v_mov_b32_e32 v67, v221
	v_lshlrev_b32_e32 v104, 16, v94
	v_and_b32_e32 v105, 0xffff0000, v94
	v_lshlrev_b32_e32 v94, 16, v95
	v_and_b32_e32 v95, 0xffff0000, v95
	v_lshlrev_b32_e32 v106, 16, v96
	v_and_b32_e32 v107, 0xffff0000, v96
	v_lshlrev_b32_e32 v96, 16, v97
	v_and_b32_e32 v97, 0xffff0000, v97
	v_lshlrev_b32_e32 v108, 16, v98
	v_and_b32_e32 v109, 0xffff0000, v98
	v_lshlrev_b32_e32 v98, 16, v99
	v_and_b32_e32 v99, 0xffff0000, v99
	v_lshlrev_b32_e32 v110, 16, v100
	v_and_b32_e32 v111, 0xffff0000, v100
	v_pk_add_f32 v[62:63], v[62:63], v[94:95]
	v_pk_add_f32 v[60:61], v[60:61], v[104:105]
	v_pk_add_f32 v[58:59], v[58:59], v[96:97]
	v_pk_add_f32 v[96:97], v[54:55], v[98:99]
	v_pk_add_f32 v[98:99], v[48:49], v[110:111]
	v_pk_mul_f32 v[48:49], v[62:63], v[62:63]
	v_pk_add_f32 v[56:57], v[56:57], v[106:107]
	v_pk_fma_f32 v[48:49], v[60:61], v[60:61], v[48:49]
	v_pk_add_f32 v[94:95], v[52:53], v[108:109]
	v_pk_fma_f32 v[48:49], v[56:57], v[56:57], v[48:49]
	v_lshlrev_b32_e32 v100, 16, v101
	v_pk_fma_f32 v[48:49], v[58:59], v[58:59], v[48:49]
	v_and_b32_e32 v101, 0xffff0000, v101
	v_pk_fma_f32 v[48:49], v[94:95], v[94:95], v[48:49]
	v_cvt_pk_bf16_f32 v52, v60, v61
	v_cvt_pk_bf16_f32 v53, v62, v63
	v_cvt_pk_bf16_f32 v54, v56, v57
	v_pk_add_f32 v[56:57], v[50:51], v[100:101]
	v_pk_fma_f32 v[48:49], v[96:97], v[96:97], v[48:49]
	v_cvt_pk_bf16_f32 v55, v58, v59
	s_nop 0
	v_pk_fma_f32 v[48:49], v[98:99], v[98:99], v[48:49]
	s_nop 0
	v_pk_fma_f32 v[48:49], v[56:57], v[56:57], v[48:49]
	s_nop 0
	v_add_f32_e32 v51, v48, v49
	ds_bpermute_b32 v60, v193, v51
	v_lshl_add_u64 v[48:49], s[20:21], 0, v[102:103]
	v_lshl_add_u64 v[58:59], v[172:173], 1, v[48:49]
	global_store_dwordx4 v[58:59], v[52:55], off
	v_cvt_pk_bf16_f32 v50, v94, v95
	s_waitcnt lgkmcnt(0)
	v_add_f32_e32 v48, v51, v60
	ds_bpermute_b32 v49, v112, v48
	v_cvt_pk_bf16_f32 v51, v96, v97
	v_cvt_pk_bf16_f32 v52, v98, v99
	v_cvt_pk_bf16_f32 v53, v56, v57
	global_store_dwordx4 v[58:59], v[50:53], off offset:256
	s_and_saveexec_b64 s[58:59], s[8:9]
	s_cbranch_execz .LBB0_453
	s_waitcnt lgkmcnt(0)
	v_add_f32_e32 v48, v48, v49
	ds_write_b32 v188, v48 offset:2048
.LBB0_453:
	s_or_b64 exec, exec, s[58:59]
	v_lshlrev_b32_e32 v50, 16, v85
	v_and_b32_e32 v51, 0xffff0000, v85
	v_lshlrev_b32_e32 v48, 16, v84
	s_waitcnt lgkmcnt(0)
	v_and_b32_e32 v49, 0xffff0000, v84
	v_pk_add_f32 v[46:47], v[46:47], v[50:51]
	v_pk_add_f32 v[48:49], v[44:45], v[48:49]
	v_pk_mul_f32 v[50:51], v[46:47], v[46:47]
	v_cvt_pk_bf16_f32 v44, v48, v49
	v_cvt_pk_bf16_f32 v45, v46, v47
	v_lshlrev_b32_e32 v46, 16, v86
	v_and_b32_e32 v47, 0xffff0000, v86
	v_pk_fma_f32 v[48:49], v[48:49], v[48:49], v[50:51]
	v_pk_add_f32 v[40:41], v[40:41], v[46:47]
	s_nop 0
	v_pk_fma_f32 v[48:49], v[40:41], v[40:41], v[48:49]
	v_cvt_pk_bf16_f32 v46, v40, v41
	v_lshlrev_b32_e32 v40, 16, v87
	v_and_b32_e32 v41, 0xffff0000, v87
	v_pk_add_f32 v[40:41], v[42:43], v[40:41]
	s_nop 0
	v_pk_fma_f32 v[42:43], v[40:41], v[40:41], v[48:49]
	v_cvt_pk_bf16_f32 v47, v40, v41
	v_lshlrev_b32_e32 v40, 16, v80
	v_and_b32_e32 v41, 0xffff0000, v80
	v_pk_add_f32 v[36:37], v[36:37], v[40:41]
	s_nop 0
	v_pk_fma_f32 v[40:41], v[36:37], v[36:37], v[42:43]
	v_lshlrev_b32_e32 v42, 16, v81
	v_and_b32_e32 v43, 0xffff0000, v81
	v_pk_add_f32 v[38:39], v[38:39], v[42:43]
	v_lshlrev_b32_e32 v42, 16, v82
	v_and_b32_e32 v43, 0xffff0000, v82
	v_pk_fma_f32 v[40:41], v[38:39], v[38:39], v[40:41]
	v_pk_add_f32 v[42:43], v[32:33], v[42:43]
	s_nop 0
	v_pk_fma_f32 v[32:33], v[42:43], v[42:43], v[40:41]
	v_lshlrev_b32_e32 v40, 16, v83
	v_and_b32_e32 v41, 0xffff0000, v83
	v_pk_add_f32 v[40:41], v[34:35], v[40:41]
	s_nop 0
	v_pk_fma_f32 v[32:33], v[40:41], v[40:41], v[32:33]
	s_nop 0
	v_add_f32_e32 v35, v32, v33
	ds_bpermute_b32 v50, v193, v35
	v_lshl_add_u64 v[32:33], s[20:21], 0, v[92:93]
	v_lshl_add_u64 v[48:49], v[172:173], 1, v[32:33]
	global_store_dwordx4 v[48:49], v[44:47], off
	v_cvt_pk_bf16_f32 v34, v36, v37
	s_waitcnt lgkmcnt(0)
	v_add_f32_e32 v32, v35, v50
	ds_bpermute_b32 v33, v112, v32
	v_cvt_pk_bf16_f32 v35, v38, v39
	v_cvt_pk_bf16_f32 v36, v42, v43
	v_cvt_pk_bf16_f32 v37, v40, v41
	global_store_dwordx4 v[48:49], v[34:37], off offset:256
	s_and_saveexec_b64 s[58:59], s[8:9]
	s_cbranch_execz .LBB0_455
	s_waitcnt lgkmcnt(0)
	v_add_f32_e32 v32, v32, v33
	ds_write_b32 v188, v32 offset:2304
.LBB0_455:
	s_or_b64 exec, exec, s[58:59]
	v_lshlrev_b32_e32 v34, 16, v77
	v_and_b32_e32 v35, 0xffff0000, v77
	v_lshlrev_b32_e32 v32, 16, v76
	s_waitcnt lgkmcnt(0)
	v_and_b32_e32 v33, 0xffff0000, v76
	v_pk_add_f32 v[30:31], v[30:31], v[34:35]
	v_pk_add_f32 v[32:33], v[28:29], v[32:33]
	v_pk_mul_f32 v[34:35], v[30:31], v[30:31]
	v_cvt_pk_bf16_f32 v28, v32, v33
	v_cvt_pk_bf16_f32 v29, v30, v31
	v_lshlrev_b32_e32 v30, 16, v78
	v_and_b32_e32 v31, 0xffff0000, v78
	v_pk_fma_f32 v[32:33], v[32:33], v[32:33], v[34:35]
	v_pk_add_f32 v[24:25], v[24:25], v[30:31]
	s_nop 0
	v_pk_fma_f32 v[32:33], v[24:25], v[24:25], v[32:33]
	v_cvt_pk_bf16_f32 v30, v24, v25
	v_lshlrev_b32_e32 v24, 16, v79
	v_and_b32_e32 v25, 0xffff0000, v79
	v_pk_add_f32 v[24:25], v[26:27], v[24:25]
	s_nop 0
	v_pk_fma_f32 v[26:27], v[24:25], v[24:25], v[32:33]
	v_cvt_pk_bf16_f32 v31, v24, v25
	v_lshlrev_b32_e32 v24, 16, v72
	v_and_b32_e32 v25, 0xffff0000, v72
	v_pk_add_f32 v[20:21], v[20:21], v[24:25]
	s_nop 0
	v_pk_fma_f32 v[24:25], v[20:21], v[20:21], v[26:27]
	v_lshlrev_b32_e32 v26, 16, v73
	v_and_b32_e32 v27, 0xffff0000, v73
	v_pk_add_f32 v[22:23], v[22:23], v[26:27]
	v_lshlrev_b32_e32 v26, 16, v74
	v_and_b32_e32 v27, 0xffff0000, v74
	v_pk_fma_f32 v[24:25], v[22:23], v[22:23], v[24:25]
	v_pk_add_f32 v[26:27], v[16:17], v[26:27]
	s_nop 0
	v_pk_fma_f32 v[16:17], v[26:27], v[26:27], v[24:25]
	v_lshlrev_b32_e32 v24, 16, v75
	v_and_b32_e32 v25, 0xffff0000, v75
	v_pk_add_f32 v[24:25], v[18:19], v[24:25]
	s_nop 0
	v_pk_fma_f32 v[16:17], v[24:25], v[24:25], v[16:17]
	s_nop 0
	v_add_f32_e32 v19, v16, v17
	ds_bpermute_b32 v34, v193, v19
	v_lshl_add_u64 v[16:17], s[20:21], 0, v[90:91]
	v_lshl_add_u64 v[32:33], v[172:173], 1, v[16:17]
	global_store_dwordx4 v[32:33], v[28:31], off
	v_cvt_pk_bf16_f32 v18, v20, v21
	s_waitcnt lgkmcnt(0)
	v_add_f32_e32 v16, v19, v34
	ds_bpermute_b32 v17, v112, v16
	v_cvt_pk_bf16_f32 v19, v22, v23
	v_cvt_pk_bf16_f32 v20, v26, v27
	v_cvt_pk_bf16_f32 v21, v24, v25
	global_store_dwordx4 v[32:33], v[18:21], off offset:256
	s_and_saveexec_b64 s[58:59], s[8:9]
	s_cbranch_execz .LBB0_457
	s_waitcnt lgkmcnt(0)
	v_add_f32_e32 v16, v16, v17
	ds_write_b32 v188, v16 offset:2560
.LBB0_457:
	s_or_b64 exec, exec, s[58:59]
	v_lshlrev_b32_e32 v18, 16, v69
	v_and_b32_e32 v19, 0xffff0000, v69
	v_lshlrev_b32_e32 v16, 16, v68
	s_waitcnt lgkmcnt(0)
	v_and_b32_e32 v17, 0xffff0000, v68
	v_pk_add_f32 v[14:15], v[14:15], v[18:19]
	v_pk_add_f32 v[16:17], v[12:13], v[16:17]
	v_pk_mul_f32 v[18:19], v[14:15], v[14:15]
	v_cvt_pk_bf16_f32 v12, v16, v17
	v_cvt_pk_bf16_f32 v13, v14, v15
	v_lshlrev_b32_e32 v14, 16, v70
	v_and_b32_e32 v15, 0xffff0000, v70
	v_pk_fma_f32 v[16:17], v[16:17], v[16:17], v[18:19]
	v_pk_add_f32 v[8:9], v[8:9], v[14:15]
	s_nop 0
	v_pk_fma_f32 v[16:17], v[8:9], v[8:9], v[16:17]
	v_cvt_pk_bf16_f32 v14, v8, v9
	v_lshlrev_b32_e32 v8, 16, v71
	v_and_b32_e32 v9, 0xffff0000, v71
	v_pk_add_f32 v[8:9], v[10:11], v[8:9]
	s_nop 0
	v_pk_fma_f32 v[10:11], v[8:9], v[8:9], v[16:17]
	v_cvt_pk_bf16_f32 v15, v8, v9
	v_lshlrev_b32_e32 v8, 16, v64
	v_and_b32_e32 v9, 0xffff0000, v64
	v_pk_add_f32 v[4:5], v[4:5], v[8:9]
	s_nop 0
	v_pk_fma_f32 v[8:9], v[4:5], v[4:5], v[10:11]
	v_lshlrev_b32_e32 v10, 16, v65
	v_and_b32_e32 v11, 0xffff0000, v65
	v_pk_add_f32 v[6:7], v[6:7], v[10:11]
	v_lshlrev_b32_e32 v10, 16, v66
	v_and_b32_e32 v11, 0xffff0000, v66
	v_pk_fma_f32 v[8:9], v[6:7], v[6:7], v[8:9]
	v_pk_add_f32 v[10:11], v[0:1], v[10:11]
	s_nop 0
	v_pk_fma_f32 v[0:1], v[10:11], v[10:11], v[8:9]
	v_lshlrev_b32_e32 v8, 16, v67
	v_and_b32_e32 v9, 0xffff0000, v67
	v_pk_add_f32 v[8:9], v[2:3], v[8:9]
	s_nop 0
	v_pk_fma_f32 v[0:1], v[8:9], v[8:9], v[0:1]
	s_nop 0
	v_add_f32_e32 v3, v0, v1
	ds_bpermute_b32 v18, v193, v3
	v_lshl_add_u64 v[0:1], s[20:21], 0, v[88:89]
	v_lshl_add_u64 v[16:17], v[172:173], 1, v[0:1]
	global_store_dwordx4 v[16:17], v[12:15], off
	v_cvt_pk_bf16_f32 v2, v4, v5
	s_waitcnt lgkmcnt(0)
	v_add_f32_e32 v0, v3, v18
	ds_bpermute_b32 v1, v112, v0
	v_cvt_pk_bf16_f32 v3, v6, v7
	v_cvt_pk_bf16_f32 v4, v10, v11
	v_cvt_pk_bf16_f32 v5, v8, v9
	global_store_dwordx4 v[16:17], v[2:5], off offset:256
	s_and_saveexec_b64 s[58:59], s[8:9]
	s_cbranch_execz .LBB0_459
	s_waitcnt lgkmcnt(0)
	v_add_f32_e32 v0, v0, v1
	ds_write_b32 v188, v0 offset:2816

.LBB0_613:
	s_lshl_b32 s21, s21, 8
	v_lshl_or_b32 v172, s20, 8, v187
	v_add_u32_e32 v176, s21, v185
	v_ashrrev_i32_e32 v173, 31, v172
	v_lshlrev_b64 v[202:203], 1, v[172:173]
	v_ashrrev_i32_e32 v177, 31, v176
	v_lshl_add_u64 v[174:175], s[24:25], 0, v[202:203]
	v_lshlrev_b64 v[204:205], 11, v[176:177]
	v_lshl_add_u64 v[128:129], v[174:175], 0, v[204:205]
	global_load_dwordx4 v[194:197], v[128:129], off
	global_load_dwordx4 v[198:201], v[128:129], off offset:256
	v_or_b32_e32 v128, 16, v176
	v_or_b32_e32 v130, 32, v176
	v_or_b32_e32 v132, 48, v176
	v_ashrrev_i32_e32 v129, 31, v128
	v_ashrrev_i32_e32 v131, 31, v130
	v_ashrrev_i32_e32 v133, 31, v132
	v_lshlrev_b64 v[182:183], 11, v[128:129]
	v_lshlrev_b64 v[180:181], 11, v[130:131]
	v_lshlrev_b64 v[178:179], 11, v[132:133]
	v_lshl_add_u64 v[128:129], v[174:175], 0, v[182:183]
	v_lshl_add_u64 v[130:131], v[174:175], 0, v[180:181]
	v_lshl_add_u64 v[206:207], v[174:175], 0, v[178:179]
	global_load_dwordx4 v[148:151], v[128:129], off
	global_load_dwordx4 v[144:147], v[128:129], off offset:256
	global_load_dwordx4 v[140:143], v[130:131], off
	global_load_dwordx4 v[136:139], v[130:131], off offset:256
	global_load_dwordx4 v[132:135], v[206:207], off
	s_nop 0
	global_load_dwordx4 v[128:131], v[206:207], off offset:256
	v_lshlrev_b64 v[222:223], 11, v[176:177]
	v_lshl_add_u64 v[224:225], v[222:223], 0, s[44:45]
	v_lshl_add_u64 v[224:225], v[174:175], 0, v[224:225]
	global_load_dwordx4 v[232:235], v[224:225], off
	global_load_dwordx4 v[236:239], v[224:225], off offset:256
	v_lshl_add_u64 v[226:227], v[222:223], 0, s[46:47]
	v_lshl_add_u64 v[226:227], v[174:175], 0, v[226:227]
	global_load_dwordx4 v[240:243], v[226:227], off
	global_load_dwordx4 v[244:247], v[226:227], off offset:256
	v_lshl_add_u64 v[224:225], v[222:223], 0, s[48:49]
	v_lshl_add_u64 v[224:225], v[174:175], 0, v[224:225]
	global_load_dwordx4 v[248:251], v[224:225], off
	global_load_dwordx4 v[252:255], v[224:225], off offset:256
	v_lshl_add_u64 v[226:227], v[222:223], 0, s[50:51]
	v_lshl_add_u64 v[226:227], v[174:175], 0, v[226:227]
	global_load_dwordx4 v[214:217], v[226:227], off
	global_load_dwordx4 v[218:221], v[226:227], off offset:256
	v_and_b32_e32 v206, 64, v159
	v_xor_b32_e32 v193, 16, v159
	v_add_u32_e32 v206, 64, v206
	v_xor_b32_e32 v207, 32, v159
	v_cmp_lt_i32_e32 vcc, v193, v206
	v_lshl_add_u64 v[204:205], s[24:25], 0, v[204:205]
	v_lshl_add_u64 v[202:203], v[204:205], 0, v[202:203]
	v_cndmask_b32_e32 v193, v159, v193, vcc
	v_cmp_lt_i32_e32 vcc, v207, v206
	v_lshlrev_b32_e32 v193, 2, v193
	s_waitcnt vmcnt(0)
	v_lshlrev_b32_e32 v204, 16, v194
	v_and_b32_e32 v205, 0xffff0000, v194
	v_lshlrev_b32_e32 v194, 16, v195
	v_and_b32_e32 v195, 0xffff0000, v195
	v_cndmask_b32_e32 v212, v159, v207, vcc
	v_lshlrev_b32_e32 v206, 16, v196
	v_and_b32_e32 v207, 0xffff0000, v196
	v_lshlrev_b32_e32 v196, 16, v197
	v_and_b32_e32 v197, 0xffff0000, v197
	v_lshlrev_b32_e32 v210, 16, v200
	v_and_b32_e32 v211, 0xffff0000, v200
	v_lshlrev_b32_e32 v200, 16, v201
	v_and_b32_e32 v201, 0xffff0000, v201
	v_pk_fma_f32 v[126:127], v[126:127], 0.5, v[194:195] op_sel_hi:[1,0,1]
	v_pk_fma_f32 v[124:125], v[124:125], 0.5, v[204:205] op_sel_hi:[1,0,1]
	v_pk_fma_f32 v[122:123], v[122:123], 0.5, v[196:197] op_sel_hi:[1,0,1]
	v_pk_fma_f32 v[196:197], v[114:115], 0.5, v[200:201] op_sel_hi:[1,0,1]
	v_pk_mul_f32 v[114:115], v[126:127], v[126:127]
	v_pk_fma_f32 v[120:121], v[120:121], 0.5, v[206:207] op_sel_hi:[1,0,1]
	v_pk_fma_f32 v[114:115], v[124:125], v[124:125], v[114:115]
	v_lshlrev_b32_e32 v208, 16, v198
	v_and_b32_e32 v209, 0xffff0000, v198
	v_pk_fma_f32 v[114:115], v[120:121], v[120:121], v[114:115]
	v_lshlrev_b32_e32 v198, 16, v199
	v_and_b32_e32 v199, 0xffff0000, v199
	v_pk_fma_f32 v[116:117], v[116:117], 0.5, v[208:209] op_sel_hi:[1,0,1]
	v_pk_fma_f32 v[114:115], v[122:123], v[122:123], v[114:115]
	v_pk_fma_f32 v[118:119], v[118:119], 0.5, v[198:199] op_sel_hi:[1,0,1]
	v_pk_fma_f32 v[114:115], v[116:117], v[116:117], v[114:115]
	v_pk_fma_f32 v[194:195], v[112:113], 0.5, v[210:211] op_sel_hi:[1,0,1]
	v_pk_fma_f32 v[114:115], v[118:119], v[118:119], v[114:115]
	v_cvt_pk_bf16_f32 v112, v124, v125
	v_cvt_pk_bf16_f32 v113, v126, v127
	s_nop 0
	v_pk_fma_f32 v[114:115], v[194:195], v[194:195], v[114:115]
	s_nop 0
	v_pk_fma_f32 v[114:115], v[196:197], v[196:197], v[114:115]
	s_nop 0
	v_add_f32_e32 v124, v114, v115
	ds_bpermute_b32 v125, v193, v124
	v_cvt_pk_bf16_f32 v114, v120, v121
	v_cvt_pk_bf16_f32 v115, v122, v123
	global_store_dwordx4 v[202:203], v[112:115], off
	v_cvt_pk_bf16_f32 v116, v116, v117
	v_cvt_pk_bf16_f32 v117, v118, v119
	v_cvt_pk_bf16_f32 v118, v194, v195
	v_cvt_pk_bf16_f32 v119, v196, v197
	global_store_dwordx4 v[202:203], v[116:119], off offset:256
	s_waitcnt lgkmcnt(0)
	v_add_f32_e32 v113, v124, v125
	v_lshlrev_b32_e32 v112, 2, v212
	ds_bpermute_b32 v114, v112, v113
	s_and_saveexec_b64 s[54:55], s[10:11]
	s_cbranch_execz .LBB0_615
	s_waitcnt lgkmcnt(0)
	v_add_f32_e32 v113, v113, v114
	ds_write_b32 v188, v113

.LBB0_621:
	s_or_b64 exec, exec, s[54:55]
	s_waitcnt lgkmcnt(0)
	v_lshlrev_b64 v[64:65], 11, v[176:177]
	v_lshl_add_u64 v[102:103], v[64:65], 0, s[44:45]
	v_lshl_add_u64 v[66:67], v[174:175], 0, v[102:103]
	v_mov_b32_e32 v94, v232
	v_mov_b32_e32 v95, v233
	v_mov_b32_e32 v96, v234
	v_mov_b32_e32 v97, v235
	v_mov_b32_e32 v98, v236
	v_mov_b32_e32 v99, v237
	v_mov_b32_e32 v100, v238
	v_mov_b32_e32 v101, v239
	v_lshl_add_u64 v[92:93], v[64:65], 0, s[46:47]
	v_lshl_add_u64 v[90:91], v[64:65], 0, s[48:49]
	v_lshl_add_u64 v[88:89], v[64:65], 0, s[50:51]
	v_lshl_add_u64 v[64:65], v[174:175], 0, v[92:93]
	v_lshl_add_u64 v[66:67], v[174:175], 0, v[90:91]
	v_lshl_add_u64 v[104:105], v[174:175], 0, v[88:89]
	v_mov_b32_e32 v84, v240
	v_mov_b32_e32 v85, v241
	v_mov_b32_e32 v86, v242
	v_mov_b32_e32 v87, v243
	v_mov_b32_e32 v80, v244
	v_mov_b32_e32 v81, v245
	v_mov_b32_e32 v82, v246
	v_mov_b32_e32 v83, v247
	v_mov_b32_e32 v76, v248
	v_mov_b32_e32 v77, v249
	v_mov_b32_e32 v78, v250
	v_mov_b32_e32 v79, v251
	v_mov_b32_e32 v72, v252
	v_mov_b32_e32 v73, v253
	v_mov_b32_e32 v74, v254
	v_mov_b32_e32 v75, v255
	v_mov_b32_e32 v68, v214
	v_mov_b32_e32 v69, v215
	v_mov_b32_e32 v70, v216
	v_mov_b32_e32 v71, v217
	s_nop 0
	v_mov_b32_e32 v64, v218
	v_mov_b32_e32 v65, v219
	v_mov_b32_e32 v66, v220
	v_mov_b32_e32 v67, v221
	v_lshlrev_b32_e32 v104, 16, v94
	v_and_b32_e32 v105, 0xffff0000, v94
	v_lshlrev_b32_e32 v94, 16, v95
	v_and_b32_e32 v95, 0xffff0000, v95
	v_lshlrev_b32_e32 v106, 16, v96
	v_and_b32_e32 v107, 0xffff0000, v96
	v_lshlrev_b32_e32 v96, 16, v97
	v_and_b32_e32 v97, 0xffff0000, v97
	v_lshlrev_b32_e32 v108, 16, v98
	v_and_b32_e32 v109, 0xffff0000, v98
	v_lshlrev_b32_e32 v98, 16, v99
	v_and_b32_e32 v99, 0xffff0000, v99
	v_lshlrev_b32_e32 v110, 16, v100
	v_and_b32_e32 v111, 0xffff0000, v100
	v_pk_fma_f32 v[62:63], v[62:63], 0.5, v[94:95] op_sel_hi:[1,0,1]
	v_pk_fma_f32 v[60:61], v[60:61], 0.5, v[104:105] op_sel_hi:[1,0,1]
	v_pk_fma_f32 v[58:59], v[58:59], 0.5, v[96:97] op_sel_hi:[1,0,1]
	v_pk_fma_f32 v[96:97], v[54:55], 0.5, v[98:99] op_sel_hi:[1,0,1]
	v_pk_fma_f32 v[98:99], v[48:49], 0.5, v[110:111] op_sel_hi:[1,0,1]
	v_pk_mul_f32 v[48:49], v[62:63], v[62:63]
	v_pk_fma_f32 v[56:57], v[56:57], 0.5, v[106:107] op_sel_hi:[1,0,1]
	v_pk_fma_f32 v[48:49], v[60:61], v[60:61], v[48:49]
	v_pk_fma_f32 v[94:95], v[52:53], 0.5, v[108:109] op_sel_hi:[1,0,1]
	v_pk_fma_f32 v[48:49], v[56:57], v[56:57], v[48:49]
	v_lshlrev_b32_e32 v100, 16, v101
	v_pk_fma_f32 v[48:49], v[58:59], v[58:59], v[48:49]
	v_and_b32_e32 v101, 0xffff0000, v101
	v_pk_fma_f32 v[48:49], v[94:95], v[94:95], v[48:49]
	v_cvt_pk_bf16_f32 v52, v60, v61
	v_cvt_pk_bf16_f32 v53, v62, v63
	v_cvt_pk_bf16_f32 v54, v56, v57
	v_pk_fma_f32 v[56:57], v[50:51], 0.5, v[100:101] op_sel_hi:[1,0,1]
	v_pk_fma_f32 v[48:49], v[96:97], v[96:97], v[48:49]
	v_cvt_pk_bf16_f32 v55, v58, v59
	s_nop 0
	v_pk_fma_f32 v[48:49], v[98:99], v[98:99], v[48:49]
	s_nop 0
	v_pk_fma_f32 v[48:49], v[56:57], v[56:57], v[48:49]
	s_nop 0
	v_add_f32_e32 v51, v48, v49
	ds_bpermute_b32 v60, v193, v51
	v_lshl_add_u64 v[48:49], s[24:25], 0, v[102:103]
	v_lshl_add_u64 v[58:59], v[172:173], 1, v[48:49]
	global_store_dwordx4 v[58:59], v[52:55], off
	v_cvt_pk_bf16_f32 v50, v94, v95
	s_waitcnt lgkmcnt(0)
	v_add_f32_e32 v48, v51, v60
	ds_bpermute_b32 v49, v112, v48
	v_cvt_pk_bf16_f32 v51, v96, v97
	v_cvt_pk_bf16_f32 v52, v98, v99
	v_cvt_pk_bf16_f32 v53, v56, v57
	global_store_dwordx4 v[58:59], v[50:53], off offset:256
	s_and_saveexec_b64 s[54:55], s[10:11]
	s_cbranch_execz .LBB0_623
	s_waitcnt lgkmcnt(0)
	v_add_f32_e32 v48, v48, v49
	ds_write_b32 v188, v48 offset:2048
.LBB0_623:
	s_or_b64 exec, exec, s[54:55]
	v_lshlrev_b32_e32 v50, 16, v85
	v_and_b32_e32 v51, 0xffff0000, v85
	v_lshlrev_b32_e32 v48, 16, v84
	s_waitcnt lgkmcnt(0)
	v_and_b32_e32 v49, 0xffff0000, v84
	v_pk_fma_f32 v[46:47], v[46:47], 0.5, v[50:51] op_sel_hi:[1,0,1]
	v_pk_fma_f32 v[48:49], v[44:45], 0.5, v[48:49] op_sel_hi:[1,0,1]
	v_pk_mul_f32 v[50:51], v[46:47], v[46:47]
	v_cvt_pk_bf16_f32 v44, v48, v49
	v_cvt_pk_bf16_f32 v45, v46, v47
	v_lshlrev_b32_e32 v46, 16, v86
	v_and_b32_e32 v47, 0xffff0000, v86
	v_pk_fma_f32 v[48:49], v[48:49], v[48:49], v[50:51]
	v_pk_fma_f32 v[40:41], v[40:41], 0.5, v[46:47] op_sel_hi:[1,0,1]
	s_nop 0
	v_pk_fma_f32 v[48:49], v[40:41], v[40:41], v[48:49]
	v_cvt_pk_bf16_f32 v46, v40, v41
	v_lshlrev_b32_e32 v40, 16, v87
	v_and_b32_e32 v41, 0xffff0000, v87
	v_pk_fma_f32 v[40:41], v[42:43], 0.5, v[40:41] op_sel_hi:[1,0,1]
	s_nop 0
	v_pk_fma_f32 v[42:43], v[40:41], v[40:41], v[48:49]
	v_cvt_pk_bf16_f32 v47, v40, v41
	v_lshlrev_b32_e32 v40, 16, v80
	v_and_b32_e32 v41, 0xffff0000, v80
	v_pk_fma_f32 v[36:37], v[36:37], 0.5, v[40:41] op_sel_hi:[1,0,1]
	s_nop 0
	v_pk_fma_f32 v[40:41], v[36:37], v[36:37], v[42:43]
	v_lshlrev_b32_e32 v42, 16, v81
	v_and_b32_e32 v43, 0xffff0000, v81
	v_pk_fma_f32 v[38:39], v[38:39], 0.5, v[42:43] op_sel_hi:[1,0,1]
	v_lshlrev_b32_e32 v42, 16, v82
	v_and_b32_e32 v43, 0xffff0000, v82
	v_pk_fma_f32 v[40:41], v[38:39], v[38:39], v[40:41]
	v_pk_fma_f32 v[42:43], v[32:33], 0.5, v[42:43] op_sel_hi:[1,0,1]
	s_nop 0
	v_pk_fma_f32 v[32:33], v[42:43], v[42:43], v[40:41]
	v_lshlrev_b32_e32 v40, 16, v83
	v_and_b32_e32 v41, 0xffff0000, v83
	v_pk_fma_f32 v[40:41], v[34:35], 0.5, v[40:41] op_sel_hi:[1,0,1]
	s_nop 0
	v_pk_fma_f32 v[32:33], v[40:41], v[40:41], v[32:33]
	s_nop 0
	v_add_f32_e32 v35, v32, v33
	ds_bpermute_b32 v50, v193, v35
	v_lshl_add_u64 v[32:33], s[24:25], 0, v[92:93]
	v_lshl_add_u64 v[48:49], v[172:173], 1, v[32:33]
	global_store_dwordx4 v[48:49], v[44:47], off
	v_cvt_pk_bf16_f32 v34, v36, v37
	s_waitcnt lgkmcnt(0)
	v_add_f32_e32 v32, v35, v50
	ds_bpermute_b32 v33, v112, v32
	v_cvt_pk_bf16_f32 v35, v38, v39
	v_cvt_pk_bf16_f32 v36, v42, v43
	v_cvt_pk_bf16_f32 v37, v40, v41
	global_store_dwordx4 v[48:49], v[34:37], off offset:256
	s_and_saveexec_b64 s[54:55], s[10:11]
	s_cbranch_execz .LBB0_625
	s_waitcnt lgkmcnt(0)
	v_add_f32_e32 v32, v32, v33
	ds_write_b32 v188, v32 offset:2304
.LBB0_625:
	s_or_b64 exec, exec, s[54:55]
	v_lshlrev_b32_e32 v34, 16, v77
	v_and_b32_e32 v35, 0xffff0000, v77
	v_lshlrev_b32_e32 v32, 16, v76
	s_waitcnt lgkmcnt(0)
	v_and_b32_e32 v33, 0xffff0000, v76
	v_pk_fma_f32 v[30:31], v[30:31], 0.5, v[34:35] op_sel_hi:[1,0,1]
	v_pk_fma_f32 v[32:33], v[28:29], 0.5, v[32:33] op_sel_hi:[1,0,1]
	v_pk_mul_f32 v[34:35], v[30:31], v[30:31]
	v_cvt_pk_bf16_f32 v28, v32, v33
	v_cvt_pk_bf16_f32 v29, v30, v31
	v_lshlrev_b32_e32 v30, 16, v78
	v_and_b32_e32 v31, 0xffff0000, v78
	v_pk_fma_f32 v[32:33], v[32:33], v[32:33], v[34:35]
	v_pk_fma_f32 v[24:25], v[24:25], 0.5, v[30:31] op_sel_hi:[1,0,1]
	s_nop 0
	v_pk_fma_f32 v[32:33], v[24:25], v[24:25], v[32:33]
	v_cvt_pk_bf16_f32 v30, v24, v25
	v_lshlrev_b32_e32 v24, 16, v79
	v_and_b32_e32 v25, 0xffff0000, v79
	v_pk_fma_f32 v[24:25], v[26:27], 0.5, v[24:25] op_sel_hi:[1,0,1]
	s_nop 0
	v_pk_fma_f32 v[26:27], v[24:25], v[24:25], v[32:33]
	v_cvt_pk_bf16_f32 v31, v24, v25
	v_lshlrev_b32_e32 v24, 16, v72
	v_and_b32_e32 v25, 0xffff0000, v72
	v_pk_fma_f32 v[20:21], v[20:21], 0.5, v[24:25] op_sel_hi:[1,0,1]
	s_nop 0
	v_pk_fma_f32 v[24:25], v[20:21], v[20:21], v[26:27]
	v_lshlrev_b32_e32 v26, 16, v73
	v_and_b32_e32 v27, 0xffff0000, v73
	v_pk_fma_f32 v[22:23], v[22:23], 0.5, v[26:27] op_sel_hi:[1,0,1]
	v_lshlrev_b32_e32 v26, 16, v74
	v_and_b32_e32 v27, 0xffff0000, v74
	v_pk_fma_f32 v[24:25], v[22:23], v[22:23], v[24:25]
	v_pk_fma_f32 v[26:27], v[16:17], 0.5, v[26:27] op_sel_hi:[1,0,1]
	s_nop 0
	v_pk_fma_f32 v[16:17], v[26:27], v[26:27], v[24:25]
	v_lshlrev_b32_e32 v24, 16, v75
	v_and_b32_e32 v25, 0xffff0000, v75
	v_pk_fma_f32 v[24:25], v[18:19], 0.5, v[24:25] op_sel_hi:[1,0,1]
	s_nop 0
	v_pk_fma_f32 v[16:17], v[24:25], v[24:25], v[16:17]
	s_nop 0
	v_add_f32_e32 v19, v16, v17
	ds_bpermute_b32 v34, v193, v19
	v_lshl_add_u64 v[16:17], s[24:25], 0, v[90:91]
	v_lshl_add_u64 v[32:33], v[172:173], 1, v[16:17]
	global_store_dwordx4 v[32:33], v[28:31], off
	v_cvt_pk_bf16_f32 v18, v20, v21
	s_waitcnt lgkmcnt(0)
	v_add_f32_e32 v16, v19, v34
	ds_bpermute_b32 v17, v112, v16
	v_cvt_pk_bf16_f32 v19, v22, v23
	v_cvt_pk_bf16_f32 v20, v26, v27
	v_cvt_pk_bf16_f32 v21, v24, v25
	global_store_dwordx4 v[32:33], v[18:21], off offset:256
	s_and_saveexec_b64 s[54:55], s[10:11]
	s_cbranch_execz .LBB0_627
	s_waitcnt lgkmcnt(0)
	v_add_f32_e32 v16, v16, v17
	ds_write_b32 v188, v16 offset:2560
.LBB0_627:
	s_or_b64 exec, exec, s[54:55]
	v_lshlrev_b32_e32 v18, 16, v69
	v_and_b32_e32 v19, 0xffff0000, v69
	v_lshlrev_b32_e32 v16, 16, v68
	s_waitcnt lgkmcnt(0)
	v_and_b32_e32 v17, 0xffff0000, v68
	v_pk_fma_f32 v[14:15], v[14:15], 0.5, v[18:19] op_sel_hi:[1,0,1]
	v_pk_fma_f32 v[16:17], v[12:13], 0.5, v[16:17] op_sel_hi:[1,0,1]
	v_pk_mul_f32 v[18:19], v[14:15], v[14:15]
	v_cvt_pk_bf16_f32 v12, v16, v17
	v_cvt_pk_bf16_f32 v13, v14, v15
	v_lshlrev_b32_e32 v14, 16, v70
	v_and_b32_e32 v15, 0xffff0000, v70
	v_pk_fma_f32 v[16:17], v[16:17], v[16:17], v[18:19]
	v_pk_fma_f32 v[8:9], v[8:9], 0.5, v[14:15] op_sel_hi:[1,0,1]
	s_nop 0
	v_pk_fma_f32 v[16:17], v[8:9], v[8:9], v[16:17]
	v_cvt_pk_bf16_f32 v14, v8, v9
	v_lshlrev_b32_e32 v8, 16, v71
	v_and_b32_e32 v9, 0xffff0000, v71
	v_pk_fma_f32 v[8:9], v[10:11], 0.5, v[8:9] op_sel_hi:[1,0,1]
	s_nop 0
	v_pk_fma_f32 v[10:11], v[8:9], v[8:9], v[16:17]
	v_cvt_pk_bf16_f32 v15, v8, v9
	v_lshlrev_b32_e32 v8, 16, v64
	v_and_b32_e32 v9, 0xffff0000, v64
	v_pk_fma_f32 v[4:5], v[4:5], 0.5, v[8:9] op_sel_hi:[1,0,1]
	s_nop 0
	v_pk_fma_f32 v[8:9], v[4:5], v[4:5], v[10:11]
	v_lshlrev_b32_e32 v10, 16, v65
	v_and_b32_e32 v11, 0xffff0000, v65
	v_pk_fma_f32 v[6:7], v[6:7], 0.5, v[10:11] op_sel_hi:[1,0,1]
	v_lshlrev_b32_e32 v10, 16, v66
	v_and_b32_e32 v11, 0xffff0000, v66
	v_pk_fma_f32 v[8:9], v[6:7], v[6:7], v[8:9]
	v_pk_fma_f32 v[10:11], v[0:1], 0.5, v[10:11] op_sel_hi:[1,0,1]
	s_nop 0
	v_pk_fma_f32 v[0:1], v[10:11], v[10:11], v[8:9]
	v_lshlrev_b32_e32 v8, 16, v67
	v_and_b32_e32 v9, 0xffff0000, v67
	v_pk_fma_f32 v[8:9], v[2:3], 0.5, v[8:9] op_sel_hi:[1,0,1]
	s_nop 0
	v_pk_fma_f32 v[0:1], v[8:9], v[8:9], v[0:1]
	s_nop 0
	v_add_f32_e32 v3, v0, v1
	ds_bpermute_b32 v18, v193, v3
	v_lshl_add_u64 v[0:1], s[24:25], 0, v[88:89]
	v_lshl_add_u64 v[16:17], v[172:173], 1, v[0:1]
	global_store_dwordx4 v[16:17], v[12:15], off
	v_cvt_pk_bf16_f32 v2, v4, v5
	s_waitcnt lgkmcnt(0)
	v_add_f32_e32 v0, v3, v18
	ds_bpermute_b32 v1, v112, v0
	v_cvt_pk_bf16_f32 v3, v6, v7
	v_cvt_pk_bf16_f32 v4, v10, v11
	v_cvt_pk_bf16_f32 v5, v8, v9
	global_store_dwordx4 v[16:17], v[2:5], off offset:256
	s_and_saveexec_b64 s[54:55], s[10:11]
	s_cbranch_execz .LBB0_629
	s_waitcnt lgkmcnt(0)
	v_add_f32_e32 v0, v0, v1
	ds_write_b32 v188, v0 offset:2816

.LBB0_1014:
	s_lshl_b32 s15, s56, 8
	v_lshl_or_b32 v172, s14, 8, v186
	v_add_u32_e32 v176, s15, v184
	v_ashrrev_i32_e32 v173, 31, v172
	v_lshlrev_b64 v[202:203], 1, v[172:173]
	v_ashrrev_i32_e32 v177, 31, v176
	v_lshl_add_u64 v[174:175], s[22:23], 0, v[202:203]
	v_lshlrev_b64 v[204:205], 11, v[176:177]
	v_lshl_add_u64 v[128:129], v[174:175], 0, v[204:205]
	global_load_dwordx4 v[194:197], v[128:129], off
	global_load_dwordx4 v[198:201], v[128:129], off offset:256
	v_or_b32_e32 v128, 16, v176
	v_or_b32_e32 v130, 32, v176
	v_or_b32_e32 v132, 48, v176
	v_ashrrev_i32_e32 v129, 31, v128
	v_ashrrev_i32_e32 v131, 31, v130
	v_ashrrev_i32_e32 v133, 31, v132
	v_lshlrev_b64 v[182:183], 11, v[128:129]
	v_lshlrev_b64 v[180:181], 11, v[130:131]
	v_lshlrev_b64 v[178:179], 11, v[132:133]
	v_lshl_add_u64 v[128:129], v[174:175], 0, v[182:183]
	v_lshl_add_u64 v[130:131], v[174:175], 0, v[180:181]
	v_lshl_add_u64 v[192:193], v[174:175], 0, v[178:179]
	global_load_dwordx4 v[148:151], v[128:129], off
	global_load_dwordx4 v[144:147], v[128:129], off offset:256
	global_load_dwordx4 v[140:143], v[130:131], off
	global_load_dwordx4 v[136:139], v[130:131], off offset:256
	global_load_dwordx4 v[132:135], v[192:193], off
	s_nop 0
	global_load_dwordx4 v[128:131], v[192:193], off offset:256
	v_lshlrev_b64 v[222:223], 11, v[176:177]
	v_lshl_add_u64 v[224:225], v[222:223], 0, s[16:17]
	v_lshl_add_u64 v[224:225], v[174:175], 0, v[224:225]
	global_load_dwordx4 v[232:235], v[224:225], off
	global_load_dwordx4 v[236:239], v[224:225], off offset:256
	v_lshl_add_u64 v[226:227], v[222:223], 0, s[30:31]
	v_lshl_add_u64 v[226:227], v[174:175], 0, v[226:227]
	global_load_dwordx4 v[240:243], v[226:227], off
	global_load_dwordx4 v[244:247], v[226:227], off offset:256
	v_lshl_add_u64 v[224:225], v[222:223], 0, s[44:45]
	v_lshl_add_u64 v[224:225], v[174:175], 0, v[224:225]
	global_load_dwordx4 v[248:251], v[224:225], off
	global_load_dwordx4 v[252:255], v[224:225], off offset:256
	v_lshl_add_u64 v[226:227], v[222:223], 0, s[46:47]
	v_lshl_add_u64 v[226:227], v[174:175], 0, v[226:227]
	global_load_dwordx4 v[214:217], v[226:227], off
	global_load_dwordx4 v[218:221], v[226:227], off offset:256
	v_and_b32_e32 v193, 64, v159
	v_xor_b32_e32 v192, 16, v159
	v_add_u32_e32 v193, 64, v193
	v_xor_b32_e32 v206, 32, v159
	v_cmp_lt_i32_e32 vcc, v192, v193
	v_lshl_add_u64 v[204:205], s[22:23], 0, v[204:205]
	v_lshl_add_u64 v[202:203], v[204:205], 0, v[202:203]
	v_cndmask_b32_e32 v192, v159, v192, vcc
	v_cmp_lt_i32_e32 vcc, v206, v193
	v_lshlrev_b32_e32 v192, 2, v192
	s_waitcnt vmcnt(0)
	v_lshlrev_b32_e32 v204, 16, v194
	v_and_b32_e32 v205, 0xffff0000, v194
	v_lshlrev_b32_e32 v194, 16, v195
	v_and_b32_e32 v195, 0xffff0000, v195
	v_cndmask_b32_e32 v193, v159, v206, vcc
	v_lshlrev_b32_e32 v206, 16, v196
	v_and_b32_e32 v207, 0xffff0000, v196
	v_lshlrev_b32_e32 v196, 16, v197
	v_and_b32_e32 v197, 0xffff0000, v197
	v_lshlrev_b32_e32 v210, 16, v200
	v_and_b32_e32 v211, 0xffff0000, v200
	v_lshlrev_b32_e32 v200, 16, v201
	v_and_b32_e32 v201, 0xffff0000, v201
	v_pk_add_f32 v[126:127], v[126:127], v[194:195]
	v_pk_add_f32 v[124:125], v[124:125], v[204:205]
	v_pk_add_f32 v[122:123], v[122:123], v[196:197]
	v_pk_add_f32 v[196:197], v[114:115], v[200:201]
	v_pk_mul_f32 v[114:115], v[126:127], v[126:127]
	v_pk_add_f32 v[120:121], v[120:121], v[206:207]
	v_pk_fma_f32 v[114:115], v[124:125], v[124:125], v[114:115]
	v_lshlrev_b32_e32 v208, 16, v198
	v_and_b32_e32 v209, 0xffff0000, v198
	v_pk_fma_f32 v[114:115], v[120:121], v[120:121], v[114:115]
	v_lshlrev_b32_e32 v198, 16, v199
	v_and_b32_e32 v199, 0xffff0000, v199
	v_pk_add_f32 v[116:117], v[116:117], v[208:209]
	v_pk_fma_f32 v[114:115], v[122:123], v[122:123], v[114:115]
	v_pk_add_f32 v[118:119], v[118:119], v[198:199]
	v_pk_fma_f32 v[114:115], v[116:117], v[116:117], v[114:115]
	v_pk_add_f32 v[194:195], v[112:113], v[210:211]
	v_pk_fma_f32 v[114:115], v[118:119], v[118:119], v[114:115]
	v_cvt_pk_bf16_f32 v112, v124, v125
	v_cvt_pk_bf16_f32 v113, v126, v127
	s_nop 0
	v_pk_fma_f32 v[114:115], v[194:195], v[194:195], v[114:115]
	s_nop 0
	v_pk_fma_f32 v[114:115], v[196:197], v[196:197], v[114:115]
	s_nop 0
	v_add_f32_e32 v124, v114, v115
	ds_bpermute_b32 v125, v192, v124
	v_cvt_pk_bf16_f32 v114, v120, v121
	v_cvt_pk_bf16_f32 v115, v122, v123
	global_store_dwordx4 v[202:203], v[112:115], off
	v_cvt_pk_bf16_f32 v116, v116, v117
	v_cvt_pk_bf16_f32 v117, v118, v119
	v_cvt_pk_bf16_f32 v118, v194, v195
	v_cvt_pk_bf16_f32 v119, v196, v197
	global_store_dwordx4 v[202:203], v[116:119], off offset:256
	s_waitcnt lgkmcnt(0)
	v_add_f32_e32 v113, v124, v125
	v_lshlrev_b32_e32 v112, 2, v193
	ds_bpermute_b32 v114, v112, v113
	s_and_saveexec_b64 s[56:57], s[6:7]
	s_cbranch_execz .LBB0_1016
	s_waitcnt lgkmcnt(0)
	v_add_f32_e32 v113, v113, v114
	ds_write_b32 v187, v113

.LBB0_1022:
	s_or_b64 exec, exec, s[56:57]
	s_waitcnt lgkmcnt(0)
	v_lshlrev_b64 v[64:65], 11, v[176:177]
	v_lshl_add_u64 v[102:103], v[64:65], 0, s[16:17]
	v_lshl_add_u64 v[66:67], v[174:175], 0, v[102:103]
	v_mov_b32_e32 v94, v232
	v_mov_b32_e32 v95, v233
	v_mov_b32_e32 v96, v234
	v_mov_b32_e32 v97, v235
	v_mov_b32_e32 v98, v236
	v_mov_b32_e32 v99, v237
	v_mov_b32_e32 v100, v238
	v_mov_b32_e32 v101, v239
	v_lshl_add_u64 v[92:93], v[64:65], 0, s[30:31]
	v_lshl_add_u64 v[90:91], v[64:65], 0, s[44:45]
	v_lshl_add_u64 v[88:89], v[64:65], 0, s[46:47]
	v_lshl_add_u64 v[64:65], v[174:175], 0, v[92:93]
	v_lshl_add_u64 v[66:67], v[174:175], 0, v[90:91]
	v_lshl_add_u64 v[104:105], v[174:175], 0, v[88:89]
	v_mov_b32_e32 v84, v240
	v_mov_b32_e32 v85, v241
	v_mov_b32_e32 v86, v242
	v_mov_b32_e32 v87, v243
	v_mov_b32_e32 v80, v244
	v_mov_b32_e32 v81, v245
	v_mov_b32_e32 v82, v246
	v_mov_b32_e32 v83, v247
	v_mov_b32_e32 v76, v248
	v_mov_b32_e32 v77, v249
	v_mov_b32_e32 v78, v250
	v_mov_b32_e32 v79, v251
	v_mov_b32_e32 v72, v252
	v_mov_b32_e32 v73, v253
	v_mov_b32_e32 v74, v254
	v_mov_b32_e32 v75, v255
	v_mov_b32_e32 v68, v214
	v_mov_b32_e32 v69, v215
	v_mov_b32_e32 v70, v216
	v_mov_b32_e32 v71, v217
	s_nop 0
	v_mov_b32_e32 v64, v218
	v_mov_b32_e32 v65, v219
	v_mov_b32_e32 v66, v220
	v_mov_b32_e32 v67, v221
	v_lshlrev_b32_e32 v104, 16, v94
	v_and_b32_e32 v105, 0xffff0000, v94
	v_lshlrev_b32_e32 v94, 16, v95
	v_and_b32_e32 v95, 0xffff0000, v95
	v_lshlrev_b32_e32 v106, 16, v96
	v_and_b32_e32 v107, 0xffff0000, v96
	v_lshlrev_b32_e32 v96, 16, v97
	v_and_b32_e32 v97, 0xffff0000, v97
	v_lshlrev_b32_e32 v108, 16, v98
	v_and_b32_e32 v109, 0xffff0000, v98
	v_lshlrev_b32_e32 v98, 16, v99
	v_and_b32_e32 v99, 0xffff0000, v99
	v_lshlrev_b32_e32 v110, 16, v100
	v_and_b32_e32 v111, 0xffff0000, v100
	v_pk_add_f32 v[62:63], v[62:63], v[94:95]
	v_pk_add_f32 v[60:61], v[60:61], v[104:105]
	v_pk_add_f32 v[58:59], v[58:59], v[96:97]
	v_pk_add_f32 v[96:97], v[54:55], v[98:99]
	v_pk_add_f32 v[98:99], v[48:49], v[110:111]
	v_pk_mul_f32 v[48:49], v[62:63], v[62:63]
	v_pk_add_f32 v[56:57], v[56:57], v[106:107]
	v_pk_fma_f32 v[48:49], v[60:61], v[60:61], v[48:49]
	v_pk_add_f32 v[94:95], v[52:53], v[108:109]
	v_pk_fma_f32 v[48:49], v[56:57], v[56:57], v[48:49]
	v_lshlrev_b32_e32 v100, 16, v101
	v_pk_fma_f32 v[48:49], v[58:59], v[58:59], v[48:49]
	v_and_b32_e32 v101, 0xffff0000, v101
	v_pk_fma_f32 v[48:49], v[94:95], v[94:95], v[48:49]
	v_cvt_pk_bf16_f32 v52, v60, v61
	v_cvt_pk_bf16_f32 v53, v62, v63
	v_cvt_pk_bf16_f32 v54, v56, v57
	v_pk_add_f32 v[56:57], v[50:51], v[100:101]
	v_pk_fma_f32 v[48:49], v[96:97], v[96:97], v[48:49]
	v_cvt_pk_bf16_f32 v55, v58, v59
	s_nop 0
	v_pk_fma_f32 v[48:49], v[98:99], v[98:99], v[48:49]
	s_nop 0
	v_pk_fma_f32 v[48:49], v[56:57], v[56:57], v[48:49]
	s_nop 0
	v_add_f32_e32 v51, v48, v49
	ds_bpermute_b32 v60, v192, v51
	v_lshl_add_u64 v[48:49], s[22:23], 0, v[102:103]
	v_lshl_add_u64 v[58:59], v[172:173], 1, v[48:49]
	global_store_dwordx4 v[58:59], v[52:55], off
	v_cvt_pk_bf16_f32 v50, v94, v95
	s_waitcnt lgkmcnt(0)
	v_add_f32_e32 v48, v51, v60
	ds_bpermute_b32 v49, v112, v48
	v_cvt_pk_bf16_f32 v51, v96, v97
	v_cvt_pk_bf16_f32 v52, v98, v99
	v_cvt_pk_bf16_f32 v53, v56, v57
	global_store_dwordx4 v[58:59], v[50:53], off offset:256
	s_and_saveexec_b64 s[56:57], s[6:7]
	s_cbranch_execz .LBB0_1024
	s_waitcnt lgkmcnt(0)
	v_add_f32_e32 v48, v48, v49
	ds_write_b32 v187, v48 offset:2048
.LBB0_1024:
	s_or_b64 exec, exec, s[56:57]
	v_lshlrev_b32_e32 v50, 16, v85
	v_and_b32_e32 v51, 0xffff0000, v85
	v_lshlrev_b32_e32 v48, 16, v84
	s_waitcnt lgkmcnt(0)
	v_and_b32_e32 v49, 0xffff0000, v84
	v_pk_add_f32 v[46:47], v[46:47], v[50:51]
	v_pk_add_f32 v[48:49], v[44:45], v[48:49]
	v_pk_mul_f32 v[50:51], v[46:47], v[46:47]
	v_cvt_pk_bf16_f32 v44, v48, v49
	v_cvt_pk_bf16_f32 v45, v46, v47
	v_lshlrev_b32_e32 v46, 16, v86
	v_and_b32_e32 v47, 0xffff0000, v86
	v_pk_fma_f32 v[48:49], v[48:49], v[48:49], v[50:51]
	v_pk_add_f32 v[40:41], v[40:41], v[46:47]
	s_nop 0
	v_pk_fma_f32 v[48:49], v[40:41], v[40:41], v[48:49]
	v_cvt_pk_bf16_f32 v46, v40, v41
	v_lshlrev_b32_e32 v40, 16, v87
	v_and_b32_e32 v41, 0xffff0000, v87
	v_pk_add_f32 v[40:41], v[42:43], v[40:41]
	s_nop 0
	v_pk_fma_f32 v[42:43], v[40:41], v[40:41], v[48:49]
	v_cvt_pk_bf16_f32 v47, v40, v41
	v_lshlrev_b32_e32 v40, 16, v80
	v_and_b32_e32 v41, 0xffff0000, v80
	v_pk_add_f32 v[36:37], v[36:37], v[40:41]
	s_nop 0
	v_pk_fma_f32 v[40:41], v[36:37], v[36:37], v[42:43]
	v_lshlrev_b32_e32 v42, 16, v81
	v_and_b32_e32 v43, 0xffff0000, v81
	v_pk_add_f32 v[38:39], v[38:39], v[42:43]
	v_lshlrev_b32_e32 v42, 16, v82
	v_and_b32_e32 v43, 0xffff0000, v82
	v_pk_fma_f32 v[40:41], v[38:39], v[38:39], v[40:41]
	v_pk_add_f32 v[42:43], v[32:33], v[42:43]
	s_nop 0
	v_pk_fma_f32 v[32:33], v[42:43], v[42:43], v[40:41]
	v_lshlrev_b32_e32 v40, 16, v83
	v_and_b32_e32 v41, 0xffff0000, v83
	v_pk_add_f32 v[40:41], v[34:35], v[40:41]
	s_nop 0
	v_pk_fma_f32 v[32:33], v[40:41], v[40:41], v[32:33]
	s_nop 0
	v_add_f32_e32 v35, v32, v33
	ds_bpermute_b32 v50, v192, v35
	v_lshl_add_u64 v[32:33], s[22:23], 0, v[92:93]
	v_lshl_add_u64 v[48:49], v[172:173], 1, v[32:33]
	global_store_dwordx4 v[48:49], v[44:47], off
	v_cvt_pk_bf16_f32 v34, v36, v37
	s_waitcnt lgkmcnt(0)
	v_add_f32_e32 v32, v35, v50
	ds_bpermute_b32 v33, v112, v32
	v_cvt_pk_bf16_f32 v35, v38, v39
	v_cvt_pk_bf16_f32 v36, v42, v43
	v_cvt_pk_bf16_f32 v37, v40, v41
	global_store_dwordx4 v[48:49], v[34:37], off offset:256
	s_and_saveexec_b64 s[56:57], s[6:7]
	s_cbranch_execz .LBB0_1026
	s_waitcnt lgkmcnt(0)
	v_add_f32_e32 v32, v32, v33
	ds_write_b32 v187, v32 offset:2304
.LBB0_1026:
	s_or_b64 exec, exec, s[56:57]
	v_lshlrev_b32_e32 v34, 16, v77
	v_and_b32_e32 v35, 0xffff0000, v77
	v_lshlrev_b32_e32 v32, 16, v76
	s_waitcnt lgkmcnt(0)
	v_and_b32_e32 v33, 0xffff0000, v76
	v_pk_add_f32 v[30:31], v[30:31], v[34:35]
	v_pk_add_f32 v[32:33], v[28:29], v[32:33]
	v_pk_mul_f32 v[34:35], v[30:31], v[30:31]
	v_cvt_pk_bf16_f32 v28, v32, v33
	v_cvt_pk_bf16_f32 v29, v30, v31
	v_lshlrev_b32_e32 v30, 16, v78
	v_and_b32_e32 v31, 0xffff0000, v78
	v_pk_fma_f32 v[32:33], v[32:33], v[32:33], v[34:35]
	v_pk_add_f32 v[24:25], v[24:25], v[30:31]
	s_nop 0
	v_pk_fma_f32 v[32:33], v[24:25], v[24:25], v[32:33]
	v_cvt_pk_bf16_f32 v30, v24, v25
	v_lshlrev_b32_e32 v24, 16, v79
	v_and_b32_e32 v25, 0xffff0000, v79
	v_pk_add_f32 v[24:25], v[26:27], v[24:25]
	s_nop 0
	v_pk_fma_f32 v[26:27], v[24:25], v[24:25], v[32:33]
	v_cvt_pk_bf16_f32 v31, v24, v25
	v_lshlrev_b32_e32 v24, 16, v72
	v_and_b32_e32 v25, 0xffff0000, v72
	v_pk_add_f32 v[20:21], v[20:21], v[24:25]
	s_nop 0
	v_pk_fma_f32 v[24:25], v[20:21], v[20:21], v[26:27]
	v_lshlrev_b32_e32 v26, 16, v73
	v_and_b32_e32 v27, 0xffff0000, v73
	v_pk_add_f32 v[22:23], v[22:23], v[26:27]
	v_lshlrev_b32_e32 v26, 16, v74
	v_and_b32_e32 v27, 0xffff0000, v74
	v_pk_fma_f32 v[24:25], v[22:23], v[22:23], v[24:25]
	v_pk_add_f32 v[26:27], v[16:17], v[26:27]
	s_nop 0
	v_pk_fma_f32 v[16:17], v[26:27], v[26:27], v[24:25]
	v_lshlrev_b32_e32 v24, 16, v75
	v_and_b32_e32 v25, 0xffff0000, v75
	v_pk_add_f32 v[24:25], v[18:19], v[24:25]
	s_nop 0
	v_pk_fma_f32 v[16:17], v[24:25], v[24:25], v[16:17]
	s_nop 0
	v_add_f32_e32 v19, v16, v17
	ds_bpermute_b32 v34, v192, v19
	v_lshl_add_u64 v[16:17], s[22:23], 0, v[90:91]
	v_lshl_add_u64 v[32:33], v[172:173], 1, v[16:17]
	global_store_dwordx4 v[32:33], v[28:31], off
	v_cvt_pk_bf16_f32 v18, v20, v21
	s_waitcnt lgkmcnt(0)
	v_add_f32_e32 v16, v19, v34
	ds_bpermute_b32 v17, v112, v16
	v_cvt_pk_bf16_f32 v19, v22, v23
	v_cvt_pk_bf16_f32 v20, v26, v27
	v_cvt_pk_bf16_f32 v21, v24, v25
	global_store_dwordx4 v[32:33], v[18:21], off offset:256
	s_and_saveexec_b64 s[56:57], s[6:7]
	s_cbranch_execz .LBB0_1028
	s_waitcnt lgkmcnt(0)
	v_add_f32_e32 v16, v16, v17
	ds_write_b32 v187, v16 offset:2560
.LBB0_1028:
	s_or_b64 exec, exec, s[56:57]
	v_lshlrev_b32_e32 v18, 16, v69
	v_and_b32_e32 v19, 0xffff0000, v69
	v_lshlrev_b32_e32 v16, 16, v68
	s_waitcnt lgkmcnt(0)
	v_and_b32_e32 v17, 0xffff0000, v68
	v_pk_add_f32 v[14:15], v[14:15], v[18:19]
	v_pk_add_f32 v[16:17], v[12:13], v[16:17]
	v_pk_mul_f32 v[18:19], v[14:15], v[14:15]
	v_cvt_pk_bf16_f32 v12, v16, v17
	v_cvt_pk_bf16_f32 v13, v14, v15
	v_lshlrev_b32_e32 v14, 16, v70
	v_and_b32_e32 v15, 0xffff0000, v70
	v_pk_fma_f32 v[16:17], v[16:17], v[16:17], v[18:19]
	v_pk_add_f32 v[8:9], v[8:9], v[14:15]
	s_nop 0
	v_pk_fma_f32 v[16:17], v[8:9], v[8:9], v[16:17]
	v_cvt_pk_bf16_f32 v14, v8, v9
	v_lshlrev_b32_e32 v8, 16, v71
	v_and_b32_e32 v9, 0xffff0000, v71
	v_pk_add_f32 v[8:9], v[10:11], v[8:9]
	s_nop 0
	v_pk_fma_f32 v[10:11], v[8:9], v[8:9], v[16:17]
	v_cvt_pk_bf16_f32 v15, v8, v9
	v_lshlrev_b32_e32 v8, 16, v64
	v_and_b32_e32 v9, 0xffff0000, v64
	v_pk_add_f32 v[4:5], v[4:5], v[8:9]
	s_nop 0
	v_pk_fma_f32 v[8:9], v[4:5], v[4:5], v[10:11]
	v_lshlrev_b32_e32 v10, 16, v65
	v_and_b32_e32 v11, 0xffff0000, v65
	v_pk_add_f32 v[6:7], v[6:7], v[10:11]
	v_lshlrev_b32_e32 v10, 16, v66
	v_and_b32_e32 v11, 0xffff0000, v66
	v_pk_fma_f32 v[8:9], v[6:7], v[6:7], v[8:9]
	v_pk_add_f32 v[10:11], v[0:1], v[10:11]
	s_nop 0
	v_pk_fma_f32 v[0:1], v[10:11], v[10:11], v[8:9]
	v_lshlrev_b32_e32 v8, 16, v67
	v_and_b32_e32 v9, 0xffff0000, v67
	v_pk_add_f32 v[8:9], v[2:3], v[8:9]
	s_nop 0
	v_pk_fma_f32 v[0:1], v[8:9], v[8:9], v[0:1]
	s_nop 0
	v_add_f32_e32 v3, v0, v1
	ds_bpermute_b32 v18, v192, v3
	v_lshl_add_u64 v[0:1], s[22:23], 0, v[88:89]
	v_lshl_add_u64 v[16:17], v[172:173], 1, v[0:1]
	global_store_dwordx4 v[16:17], v[12:15], off
	v_cvt_pk_bf16_f32 v2, v4, v5
	s_waitcnt lgkmcnt(0)
	v_add_f32_e32 v0, v3, v18
	ds_bpermute_b32 v1, v112, v0
	v_cvt_pk_bf16_f32 v3, v6, v7
	v_cvt_pk_bf16_f32 v4, v10, v11
	v_cvt_pk_bf16_f32 v5, v8, v9
	global_store_dwordx4 v[16:17], v[2:5], off offset:256
	s_and_saveexec_b64 s[56:57], s[6:7]
	s_cbranch_execz .LBB0_1030
	s_waitcnt lgkmcnt(0)
	v_add_f32_e32 v0, v0, v1
	ds_write_b32 v187, v0 offset:2816

.LBB0_1184:
	s_lshl_b32 s13, s13, 8
	v_lshl_or_b32 v172, s12, 8, v186
	v_add_u32_e32 v176, s13, v184
	v_ashrrev_i32_e32 v173, 31, v172
	v_lshlrev_b64 v[202:203], 1, v[172:173]
	v_ashrrev_i32_e32 v177, 31, v176
	v_lshl_add_u64 v[174:175], s[16:17], 0, v[202:203]
	v_lshlrev_b64 v[204:205], 11, v[176:177]
	v_lshl_add_u64 v[128:129], v[174:175], 0, v[204:205]
	global_load_dwordx4 v[194:197], v[128:129], off
	global_load_dwordx4 v[198:201], v[128:129], off offset:256
	v_or_b32_e32 v128, 16, v176
	v_or_b32_e32 v130, 32, v176
	v_or_b32_e32 v132, 48, v176
	v_ashrrev_i32_e32 v129, 31, v128
	v_ashrrev_i32_e32 v131, 31, v130
	v_ashrrev_i32_e32 v133, 31, v132
	v_lshlrev_b64 v[182:183], 11, v[128:129]
	v_lshlrev_b64 v[180:181], 11, v[130:131]
	v_lshlrev_b64 v[178:179], 11, v[132:133]
	v_lshl_add_u64 v[128:129], v[174:175], 0, v[182:183]
	v_lshl_add_u64 v[130:131], v[174:175], 0, v[180:181]
	v_lshl_add_u64 v[192:193], v[174:175], 0, v[178:179]
	global_load_dwordx4 v[148:151], v[128:129], off
	global_load_dwordx4 v[144:147], v[128:129], off offset:256
	global_load_dwordx4 v[140:143], v[130:131], off
	global_load_dwordx4 v[136:139], v[130:131], off offset:256
	global_load_dwordx4 v[132:135], v[192:193], off
	s_nop 0
	global_load_dwordx4 v[128:131], v[192:193], off offset:256
	v_lshlrev_b64 v[222:223], 11, v[176:177]
	v_lshl_add_u64 v[224:225], v[222:223], 0, s[26:27]
	v_lshl_add_u64 v[224:225], v[174:175], 0, v[224:225]
	global_load_dwordx4 v[232:235], v[224:225], off
	global_load_dwordx4 v[236:239], v[224:225], off offset:256
	v_lshl_add_u64 v[226:227], v[222:223], 0, s[28:29]
	v_lshl_add_u64 v[226:227], v[174:175], 0, v[226:227]
	global_load_dwordx4 v[240:243], v[226:227], off
	global_load_dwordx4 v[244:247], v[226:227], off offset:256
	v_lshl_add_u64 v[224:225], v[222:223], 0, s[30:31]
	v_lshl_add_u64 v[224:225], v[174:175], 0, v[224:225]
	global_load_dwordx4 v[248:251], v[224:225], off
	global_load_dwordx4 v[252:255], v[224:225], off offset:256
	v_lshl_add_u64 v[226:227], v[222:223], 0, s[44:45]
	v_lshl_add_u64 v[226:227], v[174:175], 0, v[226:227]
	global_load_dwordx4 v[214:217], v[226:227], off
	global_load_dwordx4 v[218:221], v[226:227], off offset:256
	v_and_b32_e32 v193, 64, v159
	v_xor_b32_e32 v192, 16, v159
	v_add_u32_e32 v193, 64, v193
	v_xor_b32_e32 v206, 32, v159
	v_cmp_lt_i32_e32 vcc, v192, v193
	v_lshl_add_u64 v[204:205], s[16:17], 0, v[204:205]
	v_lshl_add_u64 v[202:203], v[204:205], 0, v[202:203]
	v_cndmask_b32_e32 v192, v159, v192, vcc
	v_cmp_lt_i32_e32 vcc, v206, v193
	v_lshlrev_b32_e32 v192, 2, v192
	s_waitcnt vmcnt(0)
	v_lshlrev_b32_e32 v204, 16, v194
	v_and_b32_e32 v205, 0xffff0000, v194
	v_lshlrev_b32_e32 v194, 16, v195
	v_and_b32_e32 v195, 0xffff0000, v195
	v_cndmask_b32_e32 v193, v159, v206, vcc
	v_lshlrev_b32_e32 v206, 16, v196
	v_and_b32_e32 v207, 0xffff0000, v196
	v_lshlrev_b32_e32 v196, 16, v197
	v_and_b32_e32 v197, 0xffff0000, v197
	v_lshlrev_b32_e32 v210, 16, v200
	v_and_b32_e32 v211, 0xffff0000, v200
	v_lshlrev_b32_e32 v200, 16, v201
	v_and_b32_e32 v201, 0xffff0000, v201
	v_pk_fma_f32 v[126:127], v[126:127], 0.5, v[194:195] op_sel_hi:[1,0,1]
	v_pk_fma_f32 v[124:125], v[124:125], 0.5, v[204:205] op_sel_hi:[1,0,1]
	v_pk_fma_f32 v[122:123], v[122:123], 0.5, v[196:197] op_sel_hi:[1,0,1]
	v_pk_fma_f32 v[196:197], v[114:115], 0.5, v[200:201] op_sel_hi:[1,0,1]
	v_pk_mul_f32 v[114:115], v[126:127], v[126:127]
	v_pk_fma_f32 v[120:121], v[120:121], 0.5, v[206:207] op_sel_hi:[1,0,1]
	v_pk_fma_f32 v[114:115], v[124:125], v[124:125], v[114:115]
	v_lshlrev_b32_e32 v208, 16, v198
	v_and_b32_e32 v209, 0xffff0000, v198
	v_pk_fma_f32 v[114:115], v[120:121], v[120:121], v[114:115]
	v_lshlrev_b32_e32 v198, 16, v199
	v_and_b32_e32 v199, 0xffff0000, v199
	v_pk_fma_f32 v[116:117], v[116:117], 0.5, v[208:209] op_sel_hi:[1,0,1]
	v_pk_fma_f32 v[114:115], v[122:123], v[122:123], v[114:115]
	v_pk_fma_f32 v[118:119], v[118:119], 0.5, v[198:199] op_sel_hi:[1,0,1]
	v_pk_fma_f32 v[114:115], v[116:117], v[116:117], v[114:115]
	v_pk_fma_f32 v[194:195], v[112:113], 0.5, v[210:211] op_sel_hi:[1,0,1]
	v_pk_fma_f32 v[114:115], v[118:119], v[118:119], v[114:115]
	v_cvt_pk_bf16_f32 v112, v124, v125
	v_cvt_pk_bf16_f32 v113, v126, v127
	s_nop 0
	v_pk_fma_f32 v[114:115], v[194:195], v[194:195], v[114:115]
	s_nop 0
	v_pk_fma_f32 v[114:115], v[196:197], v[196:197], v[114:115]
	s_nop 0
	v_add_f32_e32 v124, v114, v115
	ds_bpermute_b32 v125, v192, v124
	v_cvt_pk_bf16_f32 v114, v120, v121
	v_cvt_pk_bf16_f32 v115, v122, v123
	global_store_dwordx4 v[202:203], v[112:115], off
	v_cvt_pk_bf16_f32 v116, v116, v117
	v_cvt_pk_bf16_f32 v117, v118, v119
	v_cvt_pk_bf16_f32 v118, v194, v195
	v_cvt_pk_bf16_f32 v119, v196, v197
	global_store_dwordx4 v[202:203], v[116:119], off offset:256
	s_waitcnt lgkmcnt(0)
	v_add_f32_e32 v113, v124, v125
	v_lshlrev_b32_e32 v112, 2, v193
	ds_bpermute_b32 v114, v112, v113
	s_and_saveexec_b64 s[48:49], s[4:5]
	s_cbranch_execz .LBB0_1186
	s_waitcnt lgkmcnt(0)
	v_add_f32_e32 v113, v113, v114
	ds_write_b32 v187, v113

.LBB0_1192:
	s_or_b64 exec, exec, s[48:49]
	s_waitcnt lgkmcnt(0)
	v_lshlrev_b64 v[64:65], 11, v[176:177]
	v_lshl_add_u64 v[102:103], v[64:65], 0, s[26:27]
	v_lshl_add_u64 v[66:67], v[174:175], 0, v[102:103]
	v_mov_b32_e32 v94, v232
	v_mov_b32_e32 v95, v233
	v_mov_b32_e32 v96, v234
	v_mov_b32_e32 v97, v235
	v_mov_b32_e32 v98, v236
	v_mov_b32_e32 v99, v237
	v_mov_b32_e32 v100, v238
	v_mov_b32_e32 v101, v239
	v_lshl_add_u64 v[92:93], v[64:65], 0, s[28:29]
	v_lshl_add_u64 v[90:91], v[64:65], 0, s[30:31]
	v_lshl_add_u64 v[88:89], v[64:65], 0, s[44:45]
	v_lshl_add_u64 v[64:65], v[174:175], 0, v[92:93]
	v_lshl_add_u64 v[66:67], v[174:175], 0, v[90:91]
	v_lshl_add_u64 v[104:105], v[174:175], 0, v[88:89]
	v_mov_b32_e32 v84, v240
	v_mov_b32_e32 v85, v241
	v_mov_b32_e32 v86, v242
	v_mov_b32_e32 v87, v243
	v_mov_b32_e32 v80, v244
	v_mov_b32_e32 v81, v245
	v_mov_b32_e32 v82, v246
	v_mov_b32_e32 v83, v247
	v_mov_b32_e32 v76, v248
	v_mov_b32_e32 v77, v249
	v_mov_b32_e32 v78, v250
	v_mov_b32_e32 v79, v251
	v_mov_b32_e32 v72, v252
	v_mov_b32_e32 v73, v253
	v_mov_b32_e32 v74, v254
	v_mov_b32_e32 v75, v255
	v_mov_b32_e32 v68, v214
	v_mov_b32_e32 v69, v215
	v_mov_b32_e32 v70, v216
	v_mov_b32_e32 v71, v217
	s_nop 0
	v_mov_b32_e32 v64, v218
	v_mov_b32_e32 v65, v219
	v_mov_b32_e32 v66, v220
	v_mov_b32_e32 v67, v221
	v_lshlrev_b32_e32 v104, 16, v94
	v_and_b32_e32 v105, 0xffff0000, v94
	v_lshlrev_b32_e32 v94, 16, v95
	v_and_b32_e32 v95, 0xffff0000, v95
	v_lshlrev_b32_e32 v106, 16, v96
	v_and_b32_e32 v107, 0xffff0000, v96
	v_lshlrev_b32_e32 v96, 16, v97
	v_and_b32_e32 v97, 0xffff0000, v97
	v_lshlrev_b32_e32 v108, 16, v98
	v_and_b32_e32 v109, 0xffff0000, v98
	v_lshlrev_b32_e32 v98, 16, v99
	v_and_b32_e32 v99, 0xffff0000, v99
	v_lshlrev_b32_e32 v110, 16, v100
	v_and_b32_e32 v111, 0xffff0000, v100
	v_pk_fma_f32 v[62:63], v[62:63], 0.5, v[94:95] op_sel_hi:[1,0,1]
	v_pk_fma_f32 v[60:61], v[60:61], 0.5, v[104:105] op_sel_hi:[1,0,1]
	v_pk_fma_f32 v[58:59], v[58:59], 0.5, v[96:97] op_sel_hi:[1,0,1]
	v_pk_fma_f32 v[96:97], v[54:55], 0.5, v[98:99] op_sel_hi:[1,0,1]
	v_pk_fma_f32 v[98:99], v[48:49], 0.5, v[110:111] op_sel_hi:[1,0,1]
	v_pk_mul_f32 v[48:49], v[62:63], v[62:63]
	v_pk_fma_f32 v[56:57], v[56:57], 0.5, v[106:107] op_sel_hi:[1,0,1]
	v_pk_fma_f32 v[48:49], v[60:61], v[60:61], v[48:49]
	v_pk_fma_f32 v[94:95], v[52:53], 0.5, v[108:109] op_sel_hi:[1,0,1]
	v_pk_fma_f32 v[48:49], v[56:57], v[56:57], v[48:49]
	v_lshlrev_b32_e32 v100, 16, v101
	v_pk_fma_f32 v[48:49], v[58:59], v[58:59], v[48:49]
	v_and_b32_e32 v101, 0xffff0000, v101
	v_pk_fma_f32 v[48:49], v[94:95], v[94:95], v[48:49]
	v_cvt_pk_bf16_f32 v52, v60, v61
	v_cvt_pk_bf16_f32 v53, v62, v63
	v_cvt_pk_bf16_f32 v54, v56, v57
	v_pk_fma_f32 v[56:57], v[50:51], 0.5, v[100:101] op_sel_hi:[1,0,1]
	v_pk_fma_f32 v[48:49], v[96:97], v[96:97], v[48:49]
	v_cvt_pk_bf16_f32 v55, v58, v59
	s_nop 0
	v_pk_fma_f32 v[48:49], v[98:99], v[98:99], v[48:49]
	s_nop 0
	v_pk_fma_f32 v[48:49], v[56:57], v[56:57], v[48:49]
	s_nop 0
	v_add_f32_e32 v51, v48, v49
	ds_bpermute_b32 v60, v192, v51
	v_lshl_add_u64 v[48:49], s[16:17], 0, v[102:103]
	v_lshl_add_u64 v[58:59], v[172:173], 1, v[48:49]
	global_store_dwordx4 v[58:59], v[52:55], off
	v_cvt_pk_bf16_f32 v50, v94, v95
	s_waitcnt lgkmcnt(0)
	v_add_f32_e32 v48, v51, v60
	ds_bpermute_b32 v49, v112, v48
	v_cvt_pk_bf16_f32 v51, v96, v97
	v_cvt_pk_bf16_f32 v52, v98, v99
	v_cvt_pk_bf16_f32 v53, v56, v57
	global_store_dwordx4 v[58:59], v[50:53], off offset:256
	s_and_saveexec_b64 s[48:49], s[4:5]
	s_cbranch_execz .LBB0_1194
	s_waitcnt lgkmcnt(0)
	v_add_f32_e32 v48, v48, v49
	ds_write_b32 v187, v48 offset:2048
.LBB0_1194:
	s_or_b64 exec, exec, s[48:49]
	v_lshlrev_b32_e32 v50, 16, v85
	v_and_b32_e32 v51, 0xffff0000, v85
	v_lshlrev_b32_e32 v48, 16, v84
	s_waitcnt lgkmcnt(0)
	v_and_b32_e32 v49, 0xffff0000, v84
	v_pk_fma_f32 v[46:47], v[46:47], 0.5, v[50:51] op_sel_hi:[1,0,1]
	v_pk_fma_f32 v[48:49], v[44:45], 0.5, v[48:49] op_sel_hi:[1,0,1]
	v_pk_mul_f32 v[50:51], v[46:47], v[46:47]
	v_cvt_pk_bf16_f32 v44, v48, v49
	v_cvt_pk_bf16_f32 v45, v46, v47
	v_lshlrev_b32_e32 v46, 16, v86
	v_and_b32_e32 v47, 0xffff0000, v86
	v_pk_fma_f32 v[48:49], v[48:49], v[48:49], v[50:51]
	v_pk_fma_f32 v[40:41], v[40:41], 0.5, v[46:47] op_sel_hi:[1,0,1]
	s_nop 0
	v_pk_fma_f32 v[48:49], v[40:41], v[40:41], v[48:49]
	v_cvt_pk_bf16_f32 v46, v40, v41
	v_lshlrev_b32_e32 v40, 16, v87
	v_and_b32_e32 v41, 0xffff0000, v87
	v_pk_fma_f32 v[40:41], v[42:43], 0.5, v[40:41] op_sel_hi:[1,0,1]
	s_nop 0
	v_pk_fma_f32 v[42:43], v[40:41], v[40:41], v[48:49]
	v_cvt_pk_bf16_f32 v47, v40, v41
	v_lshlrev_b32_e32 v40, 16, v80
	v_and_b32_e32 v41, 0xffff0000, v80
	v_pk_fma_f32 v[36:37], v[36:37], 0.5, v[40:41] op_sel_hi:[1,0,1]
	s_nop 0
	v_pk_fma_f32 v[40:41], v[36:37], v[36:37], v[42:43]
	v_lshlrev_b32_e32 v42, 16, v81
	v_and_b32_e32 v43, 0xffff0000, v81
	v_pk_fma_f32 v[38:39], v[38:39], 0.5, v[42:43] op_sel_hi:[1,0,1]
	v_lshlrev_b32_e32 v42, 16, v82
	v_and_b32_e32 v43, 0xffff0000, v82
	v_pk_fma_f32 v[40:41], v[38:39], v[38:39], v[40:41]
	v_pk_fma_f32 v[42:43], v[32:33], 0.5, v[42:43] op_sel_hi:[1,0,1]
	s_nop 0
	v_pk_fma_f32 v[32:33], v[42:43], v[42:43], v[40:41]
	v_lshlrev_b32_e32 v40, 16, v83
	v_and_b32_e32 v41, 0xffff0000, v83
	v_pk_fma_f32 v[40:41], v[34:35], 0.5, v[40:41] op_sel_hi:[1,0,1]
	s_nop 0
	v_pk_fma_f32 v[32:33], v[40:41], v[40:41], v[32:33]
	s_nop 0
	v_add_f32_e32 v35, v32, v33
	ds_bpermute_b32 v50, v192, v35
	v_lshl_add_u64 v[32:33], s[16:17], 0, v[92:93]
	v_lshl_add_u64 v[48:49], v[172:173], 1, v[32:33]
	global_store_dwordx4 v[48:49], v[44:47], off
	v_cvt_pk_bf16_f32 v34, v36, v37
	s_waitcnt lgkmcnt(0)
	v_add_f32_e32 v32, v35, v50
	ds_bpermute_b32 v33, v112, v32
	v_cvt_pk_bf16_f32 v35, v38, v39
	v_cvt_pk_bf16_f32 v36, v42, v43
	v_cvt_pk_bf16_f32 v37, v40, v41
	global_store_dwordx4 v[48:49], v[34:37], off offset:256
	s_and_saveexec_b64 s[48:49], s[4:5]
	s_cbranch_execz .LBB0_1196
	s_waitcnt lgkmcnt(0)
	v_add_f32_e32 v32, v32, v33
	ds_write_b32 v187, v32 offset:2304
.LBB0_1196:
	s_or_b64 exec, exec, s[48:49]
	v_lshlrev_b32_e32 v34, 16, v77
	v_and_b32_e32 v35, 0xffff0000, v77
	v_lshlrev_b32_e32 v32, 16, v76
	s_waitcnt lgkmcnt(0)
	v_and_b32_e32 v33, 0xffff0000, v76
	v_pk_fma_f32 v[30:31], v[30:31], 0.5, v[34:35] op_sel_hi:[1,0,1]
	v_pk_fma_f32 v[32:33], v[28:29], 0.5, v[32:33] op_sel_hi:[1,0,1]
	v_pk_mul_f32 v[34:35], v[30:31], v[30:31]
	v_cvt_pk_bf16_f32 v28, v32, v33
	v_cvt_pk_bf16_f32 v29, v30, v31
	v_lshlrev_b32_e32 v30, 16, v78
	v_and_b32_e32 v31, 0xffff0000, v78
	v_pk_fma_f32 v[32:33], v[32:33], v[32:33], v[34:35]
	v_pk_fma_f32 v[24:25], v[24:25], 0.5, v[30:31] op_sel_hi:[1,0,1]
	s_nop 0
	v_pk_fma_f32 v[32:33], v[24:25], v[24:25], v[32:33]
	v_cvt_pk_bf16_f32 v30, v24, v25
	v_lshlrev_b32_e32 v24, 16, v79
	v_and_b32_e32 v25, 0xffff0000, v79
	v_pk_fma_f32 v[24:25], v[26:27], 0.5, v[24:25] op_sel_hi:[1,0,1]
	s_nop 0
	v_pk_fma_f32 v[26:27], v[24:25], v[24:25], v[32:33]
	v_cvt_pk_bf16_f32 v31, v24, v25
	v_lshlrev_b32_e32 v24, 16, v72
	v_and_b32_e32 v25, 0xffff0000, v72
	v_pk_fma_f32 v[20:21], v[20:21], 0.5, v[24:25] op_sel_hi:[1,0,1]
	s_nop 0
	v_pk_fma_f32 v[24:25], v[20:21], v[20:21], v[26:27]
	v_lshlrev_b32_e32 v26, 16, v73
	v_and_b32_e32 v27, 0xffff0000, v73
	v_pk_fma_f32 v[22:23], v[22:23], 0.5, v[26:27] op_sel_hi:[1,0,1]
	v_lshlrev_b32_e32 v26, 16, v74
	v_and_b32_e32 v27, 0xffff0000, v74
	v_pk_fma_f32 v[24:25], v[22:23], v[22:23], v[24:25]
	v_pk_fma_f32 v[26:27], v[16:17], 0.5, v[26:27] op_sel_hi:[1,0,1]
	s_nop 0
	v_pk_fma_f32 v[16:17], v[26:27], v[26:27], v[24:25]
	v_lshlrev_b32_e32 v24, 16, v75
	v_and_b32_e32 v25, 0xffff0000, v75
	v_pk_fma_f32 v[24:25], v[18:19], 0.5, v[24:25] op_sel_hi:[1,0,1]
	s_nop 0
	v_pk_fma_f32 v[16:17], v[24:25], v[24:25], v[16:17]
	s_nop 0
	v_add_f32_e32 v19, v16, v17
	ds_bpermute_b32 v34, v192, v19
	v_lshl_add_u64 v[16:17], s[16:17], 0, v[90:91]
	v_lshl_add_u64 v[32:33], v[172:173], 1, v[16:17]
	global_store_dwordx4 v[32:33], v[28:31], off
	v_cvt_pk_bf16_f32 v18, v20, v21
	s_waitcnt lgkmcnt(0)
	v_add_f32_e32 v16, v19, v34
	ds_bpermute_b32 v17, v112, v16
	v_cvt_pk_bf16_f32 v19, v22, v23
	v_cvt_pk_bf16_f32 v20, v26, v27
	v_cvt_pk_bf16_f32 v21, v24, v25
	global_store_dwordx4 v[32:33], v[18:21], off offset:256
	s_and_saveexec_b64 s[48:49], s[4:5]
	s_cbranch_execz .LBB0_1198
	s_waitcnt lgkmcnt(0)
	v_add_f32_e32 v16, v16, v17
	ds_write_b32 v187, v16 offset:2560
.LBB0_1198:
	s_or_b64 exec, exec, s[48:49]
	v_lshlrev_b32_e32 v18, 16, v69
	v_and_b32_e32 v19, 0xffff0000, v69
	v_lshlrev_b32_e32 v16, 16, v68
	s_waitcnt lgkmcnt(0)
	v_and_b32_e32 v17, 0xffff0000, v68
	v_pk_fma_f32 v[14:15], v[14:15], 0.5, v[18:19] op_sel_hi:[1,0,1]
	v_pk_fma_f32 v[16:17], v[12:13], 0.5, v[16:17] op_sel_hi:[1,0,1]
	v_pk_mul_f32 v[18:19], v[14:15], v[14:15]
	v_cvt_pk_bf16_f32 v12, v16, v17
	v_cvt_pk_bf16_f32 v13, v14, v15
	v_lshlrev_b32_e32 v14, 16, v70
	v_and_b32_e32 v15, 0xffff0000, v70
	v_pk_fma_f32 v[16:17], v[16:17], v[16:17], v[18:19]
	v_pk_fma_f32 v[8:9], v[8:9], 0.5, v[14:15] op_sel_hi:[1,0,1]
	s_nop 0
	v_pk_fma_f32 v[16:17], v[8:9], v[8:9], v[16:17]
	v_cvt_pk_bf16_f32 v14, v8, v9
	v_lshlrev_b32_e32 v8, 16, v71
	v_and_b32_e32 v9, 0xffff0000, v71
	v_pk_fma_f32 v[8:9], v[10:11], 0.5, v[8:9] op_sel_hi:[1,0,1]
	s_nop 0
	v_pk_fma_f32 v[10:11], v[8:9], v[8:9], v[16:17]
	v_cvt_pk_bf16_f32 v15, v8, v9
	v_lshlrev_b32_e32 v8, 16, v64
	v_and_b32_e32 v9, 0xffff0000, v64
	v_pk_fma_f32 v[4:5], v[4:5], 0.5, v[8:9] op_sel_hi:[1,0,1]
	s_nop 0
	v_pk_fma_f32 v[8:9], v[4:5], v[4:5], v[10:11]
	v_lshlrev_b32_e32 v10, 16, v65
	v_and_b32_e32 v11, 0xffff0000, v65
	v_pk_fma_f32 v[6:7], v[6:7], 0.5, v[10:11] op_sel_hi:[1,0,1]
	v_lshlrev_b32_e32 v10, 16, v66
	v_and_b32_e32 v11, 0xffff0000, v66
	v_pk_fma_f32 v[8:9], v[6:7], v[6:7], v[8:9]
	v_pk_fma_f32 v[10:11], v[0:1], 0.5, v[10:11] op_sel_hi:[1,0,1]
	s_nop 0
	v_pk_fma_f32 v[0:1], v[10:11], v[10:11], v[8:9]
	v_lshlrev_b32_e32 v8, 16, v67
	v_and_b32_e32 v9, 0xffff0000, v67
	v_pk_fma_f32 v[8:9], v[2:3], 0.5, v[8:9] op_sel_hi:[1,0,1]
	s_nop 0
	v_pk_fma_f32 v[0:1], v[8:9], v[8:9], v[0:1]
	s_nop 0
	v_add_f32_e32 v3, v0, v1
	ds_bpermute_b32 v18, v192, v3
	v_lshl_add_u64 v[0:1], s[16:17], 0, v[88:89]
	v_lshl_add_u64 v[16:17], v[172:173], 1, v[0:1]
	global_store_dwordx4 v[16:17], v[12:15], off
	v_cvt_pk_bf16_f32 v2, v4, v5
	s_waitcnt lgkmcnt(0)
	v_add_f32_e32 v0, v3, v18
	ds_bpermute_b32 v1, v112, v0
	v_cvt_pk_bf16_f32 v3, v6, v7
	v_cvt_pk_bf16_f32 v4, v10, v11
	v_cvt_pk_bf16_f32 v5, v8, v9
	global_store_dwordx4 v[16:17], v[2:5], off offset:256
	s_and_saveexec_b64 s[48:49], s[4:5]
	s_cbranch_execz .LBB0_1200
	s_waitcnt lgkmcnt(0)
	v_add_f32_e32 v0, v0, v1
	ds_write_b32 v187, v0 offset:2816
